# v83 without s_setprio in the GEMM K-loops (priority has no effect in GEMM) and duplicate SGPR snapshots removed
# baseline (speedup 1.0000x reference)
.LBB0_173:
	ds_read_b128 v[144:147], v155
	ds_read_b128 v[148:151], v155 offset:1024
	ds_read_b128 v[158:161], v155 offset:2048
	ds_read_b128 v[162:165], v155 offset:3072
	ds_read_b128 v[166:169], v156
	ds_read_b128 v[170:173], v156 offset:1024
	ds_read_b128 v[174:177], v156 offset:2048
	ds_read_b128 v[178:181], v156 offset:3072
	s_add_u32 s68, s66, 0xfff80080
	s_addc_u32 s69, s67, -1
	s_cmp_eq_u32 s77, 28
	s_cselect_b32 s71, s55, s69
	s_cselect_b32 s70, s59, s68
	s_cselect_b32 s69, s57, s76
	s_cselect_b32 s68, s65, s73
	s_add_i32 m0, s25, 0xc000
	ds_read_b128 v[182:185], v157
	ds_read_b128 v[186:189], v157 offset:1024
	ds_read_b128 v[190:193], v157 offset:2048
	ds_read_b128 v[194:197], v157 offset:3072
	ds_read_b128 v[198:201], v157 offset:4096
	ds_read_b128 v[202:205], v157 offset:5120
	ds_read_b128 v[206:209], v157 offset:6144
	global_load_lds_dwordx4 v136, s[66:67]
	s_add_i32 m0, s25, 0xe000
	ds_read_b128 v[210:213], v157 offset:7168
	global_load_lds_dwordx4 v138, s[66:67]
	s_waitcnt vmcnt(8) lgkmcnt(0)
	s_barrier
	v_mfma_i32_16x16x64_i8 v[124:127], v[144:147], v[182:185], v[124:127]
	v_mfma_i32_16x16x64_i8 v[116:119], v[158:161], v[182:185], v[116:119]
	v_mfma_i32_16x16x64_i8 v[108:111], v[144:147], v[190:193], v[108:111]
	v_mfma_i32_16x16x64_i8 v[100:103], v[158:161], v[190:193], v[100:103]
	v_mfma_i32_16x16x64_i8 v[92:95], v[144:147], v[198:201], v[92:95]
	v_mfma_i32_16x16x64_i8 v[84:87], v[158:161], v[198:201], v[84:87]
	v_mfma_i32_16x16x64_i8 v[76:79], v[144:147], v[206:209], v[76:79]
	v_mfma_i32_16x16x64_i8 v[68:71], v[158:161], v[206:209], v[68:71]
	v_mfma_i32_16x16x64_i8 v[124:127], v[148:151], v[186:189], v[124:127]
	v_mfma_i32_16x16x64_i8 v[116:119], v[162:165], v[186:189], v[116:119]
	v_mfma_i32_16x16x64_i8 v[108:111], v[148:151], v[194:197], v[108:111]
	v_mfma_i32_16x16x64_i8 v[100:103], v[162:165], v[194:197], v[100:103]
	v_mfma_i32_16x16x64_i8 v[92:95], v[148:151], v[202:205], v[92:95]
	v_mfma_i32_16x16x64_i8 v[84:87], v[162:165], v[202:205], v[84:87]
	v_mfma_i32_16x16x64_i8 v[76:79], v[148:151], v[210:213], v[76:79]
	v_mfma_i32_16x16x64_i8 v[68:71], v[162:165], v[210:213], v[68:71]
	v_mfma_i32_16x16x64_i8 v[120:123], v[166:169], v[182:185], v[120:123]
	v_mfma_i32_16x16x64_i8 v[112:115], v[174:177], v[182:185], v[112:115]
	v_mfma_i32_16x16x64_i8 v[104:107], v[166:169], v[190:193], v[104:107]
	v_mfma_i32_16x16x64_i8 v[96:99], v[174:177], v[190:193], v[96:99]
	v_mfma_i32_16x16x64_i8 v[88:91], v[166:169], v[198:201], v[88:91]
	v_mfma_i32_16x16x64_i8 v[80:83], v[174:177], v[198:201], v[80:83]
	v_mfma_i32_16x16x64_i8 v[72:75], v[166:169], v[206:209], v[72:75]
	v_mfma_i32_16x16x64_i8 v[64:67], v[174:177], v[206:209], v[64:67]
	v_mfma_i32_16x16x64_i8 v[120:123], v[170:173], v[186:189], v[120:123]
	v_mfma_i32_16x16x64_i8 v[112:115], v[178:181], v[186:189], v[112:115]
	v_mfma_i32_16x16x64_i8 v[104:107], v[170:173], v[194:197], v[104:107]
	v_mfma_i32_16x16x64_i8 v[96:99], v[178:181], v[194:197], v[96:99]
	v_mfma_i32_16x16x64_i8 v[88:91], v[170:173], v[202:205], v[88:91]
	v_mfma_i32_16x16x64_i8 v[80:83], v[178:181], v[202:205], v[80:83]
	v_mfma_i32_16x16x64_i8 v[72:75], v[170:173], v[210:213], v[72:75]
	v_mfma_i32_16x16x64_i8 v[64:67], v[178:181], v[210:213], v[64:67]
	s_barrier
	s_add_i32 s78, s35, s13
	s_mov_b32 m0, s78
	ds_read_b128 v[182:185], v157 offset:16384
	ds_read_b128 v[186:189], v157 offset:17408
	ds_read_b128 v[190:193], v157 offset:18432
	ds_read_b128 v[194:197], v157 offset:19456
	ds_read_b128 v[198:201], v157 offset:20480
	global_load_lds_dwordx4 v132, s[68:69]
	s_add_i32 m0, s78, 0x2000
	s_add_u32 s78, s68, 0x80000
	s_mov_b64 s[98:99], s[68:69]
	s_addc_u32 s79, s69, 0
	s_add_i32 s81, s52, s13
	global_load_lds_dwordx4 v128, s[98:99]
	s_mov_b32 m0, s81
	s_mov_b64 s[100:101], s[70:71]
	global_load_lds_dwordx4 v132, s[78:79]
	s_add_i32 m0, s81, 0x2000
	ds_read_b128 v[202:205], v157 offset:21504
	global_load_lds_dwordx4 v128, s[78:79]
	s_mov_b32 m0, s25
	ds_read_b128 v[206:209], v157 offset:22528
	global_load_lds_dwordx4 v134, s[100:101]
	s_mov_b32 m0, s26
	ds_read_b128 v[210:213], v157 offset:23552
	global_load_lds_dwordx4 v130, s[100:101]
	s_waitcnt vmcnt(8) lgkmcnt(0)
	s_barrier
	v_mfma_i32_16x16x64_i8 v[60:63], v[144:147], v[182:185], v[60:63]
	v_mfma_i32_16x16x64_i8 v[52:55], v[158:161], v[182:185], v[52:55]
	v_mfma_i32_16x16x64_i8 v[44:47], v[144:147], v[190:193], v[44:47]
	v_mfma_i32_16x16x64_i8 v[36:39], v[158:161], v[190:193], v[36:39]
	v_mfma_i32_16x16x64_i8 v[28:31], v[144:147], v[198:201], v[28:31]
	v_mfma_i32_16x16x64_i8 v[20:23], v[158:161], v[198:201], v[20:23]
	v_mfma_i32_16x16x64_i8 v[12:15], v[144:147], v[206:209], v[12:15]
	v_mfma_i32_16x16x64_i8 v[4:7], v[158:161], v[206:209], v[4:7]
	v_mfma_i32_16x16x64_i8 v[60:63], v[148:151], v[186:189], v[60:63]
	v_mfma_i32_16x16x64_i8 v[52:55], v[162:165], v[186:189], v[52:55]
	v_mfma_i32_16x16x64_i8 v[44:47], v[148:151], v[194:197], v[44:47]
	v_mfma_i32_16x16x64_i8 v[36:39], v[162:165], v[194:197], v[36:39]
	v_mfma_i32_16x16x64_i8 v[28:31], v[148:151], v[202:205], v[28:31]
	v_mfma_i32_16x16x64_i8 v[20:23], v[162:165], v[202:205], v[20:23]
	v_mfma_i32_16x16x64_i8 v[12:15], v[148:151], v[210:213], v[12:15]
	v_mfma_i32_16x16x64_i8 v[4:7], v[162:165], v[210:213], v[4:7]
	v_mfma_i32_16x16x64_i8 v[56:59], v[166:169], v[182:185], v[56:59]
	v_mfma_i32_16x16x64_i8 v[48:51], v[174:177], v[182:185], v[48:51]
	v_mfma_i32_16x16x64_i8 v[40:43], v[166:169], v[190:193], v[40:43]
	v_mfma_i32_16x16x64_i8 v[32:35], v[174:177], v[190:193], v[32:35]
	v_mfma_i32_16x16x64_i8 v[24:27], v[166:169], v[198:201], v[24:27]
	v_mfma_i32_16x16x64_i8 v[16:19], v[174:177], v[198:201], v[16:19]
	v_mfma_i32_16x16x64_i8 v[8:11], v[166:169], v[206:209], v[8:11]
	v_mfma_i32_16x16x64_i8 v[0:3], v[174:177], v[206:209], v[0:3]
	v_mfma_i32_16x16x64_i8 v[56:59], v[170:173], v[186:189], v[56:59]
	v_mfma_i32_16x16x64_i8 v[48:51], v[178:181], v[186:189], v[48:51]
	v_mfma_i32_16x16x64_i8 v[40:43], v[170:173], v[194:197], v[40:43]
	v_mfma_i32_16x16x64_i8 v[32:35], v[178:181], v[194:197], v[32:35]
	v_mfma_i32_16x16x64_i8 v[24:27], v[170:173], v[202:205], v[24:27]
	v_mfma_i32_16x16x64_i8 v[16:19], v[178:181], v[202:205], v[16:19]
	v_mfma_i32_16x16x64_i8 v[8:11], v[170:173], v[210:213], v[8:11]
	v_mfma_i32_16x16x64_i8 v[0:3], v[178:181], v[210:213], v[0:3]
	s_barrier
	s_add_i32 s78, 0, 0x18000
	s_add_i32 s79, 0, 0x1c000
	ds_read_b128 v[144:147], v155 offset:32768
	ds_read_b128 v[148:151], v155 offset:33792
	ds_read_b128 v[158:161], v155 offset:34816
	ds_read_b128 v[162:165], v155 offset:35840
	ds_read_b128 v[166:169], v156 offset:32768
	ds_read_b128 v[170:173], v156 offset:33792
	ds_read_b128 v[174:177], v156 offset:34816
	ds_read_b128 v[178:181], v156 offset:35840
	s_add_u32 s70, s70, 0x80000
	s_addc_u32 s71, s71, 0
	s_mov_b32 m0, s27
	ds_read_b128 v[182:185], v157 offset:32768
	ds_read_b128 v[186:189], v157 offset:33792
	ds_read_b128 v[190:193], v157 offset:34816
	ds_read_b128 v[194:197], v157 offset:35840
	ds_read_b128 v[198:201], v157 offset:36864
	ds_read_b128 v[202:205], v157 offset:37888
	ds_read_b128 v[206:209], v157 offset:38912
	global_load_lds_dwordx4 v134, s[70:71]
	s_mov_b32 m0, s28
	ds_read_b128 v[210:213], v157 offset:39936
	global_load_lds_dwordx4 v130, s[70:71]
	s_waitcnt vmcnt(8) lgkmcnt(0)
	s_barrier
	v_mfma_i32_16x16x64_i8 v[124:127], v[144:147], v[182:185], v[124:127]
	v_mfma_i32_16x16x64_i8 v[116:119], v[158:161], v[182:185], v[116:119]
	v_mfma_i32_16x16x64_i8 v[108:111], v[144:147], v[190:193], v[108:111]
	v_mfma_i32_16x16x64_i8 v[100:103], v[158:161], v[190:193], v[100:103]
	v_mfma_i32_16x16x64_i8 v[92:95], v[144:147], v[198:201], v[92:95]
	v_mfma_i32_16x16x64_i8 v[84:87], v[158:161], v[198:201], v[84:87]
	v_mfma_i32_16x16x64_i8 v[76:79], v[144:147], v[206:209], v[76:79]
	v_mfma_i32_16x16x64_i8 v[68:71], v[158:161], v[206:209], v[68:71]
	v_mfma_i32_16x16x64_i8 v[124:127], v[148:151], v[186:189], v[124:127]
	v_mfma_i32_16x16x64_i8 v[116:119], v[162:165], v[186:189], v[116:119]
	v_mfma_i32_16x16x64_i8 v[108:111], v[148:151], v[194:197], v[108:111]
	v_mfma_i32_16x16x64_i8 v[100:103], v[162:165], v[194:197], v[100:103]
	v_mfma_i32_16x16x64_i8 v[92:95], v[148:151], v[202:205], v[92:95]
	v_mfma_i32_16x16x64_i8 v[84:87], v[162:165], v[202:205], v[84:87]
	v_mfma_i32_16x16x64_i8 v[76:79], v[148:151], v[210:213], v[76:79]
	v_mfma_i32_16x16x64_i8 v[68:71], v[162:165], v[210:213], v[68:71]
	v_mfma_i32_16x16x64_i8 v[120:123], v[166:169], v[182:185], v[120:123]
	v_mfma_i32_16x16x64_i8 v[112:115], v[174:177], v[182:185], v[112:115]
	v_mfma_i32_16x16x64_i8 v[104:107], v[166:169], v[190:193], v[104:107]
	v_mfma_i32_16x16x64_i8 v[96:99], v[174:177], v[190:193], v[96:99]
	v_mfma_i32_16x16x64_i8 v[88:91], v[166:169], v[198:201], v[88:91]
	v_mfma_i32_16x16x64_i8 v[80:83], v[174:177], v[198:201], v[80:83]
	v_mfma_i32_16x16x64_i8 v[72:75], v[166:169], v[206:209], v[72:75]
	v_mfma_i32_16x16x64_i8 v[64:67], v[174:177], v[206:209], v[64:67]
	v_mfma_i32_16x16x64_i8 v[120:123], v[170:173], v[186:189], v[120:123]
	v_mfma_i32_16x16x64_i8 v[112:115], v[178:181], v[186:189], v[112:115]
	v_mfma_i32_16x16x64_i8 v[104:107], v[170:173], v[194:197], v[104:107]
	v_mfma_i32_16x16x64_i8 v[96:99], v[178:181], v[194:197], v[96:99]
	v_mfma_i32_16x16x64_i8 v[88:91], v[170:173], v[202:205], v[88:91]
	v_mfma_i32_16x16x64_i8 v[80:83], v[178:181], v[202:205], v[80:83]
	v_mfma_i32_16x16x64_i8 v[72:75], v[170:173], v[210:213], v[72:75]
	v_mfma_i32_16x16x64_i8 v[64:67], v[178:181], v[210:213], v[64:67]
	s_barrier
	s_add_i32 s70, s78, s13
	s_add_i32 m0, s70, -128
	ds_read_b128 v[182:185], v157 offset:49152
	ds_read_b128 v[186:189], v157 offset:50176
	ds_read_b128 v[190:193], v157 offset:51200
	ds_read_b128 v[194:197], v157 offset:52224
	global_load_lds_dwordx4 v132, s[68:69] offset:128
	s_add_i32 m0, s70, 8064
	s_add_u32 s68, s68, 0x80080
	s_addc_u32 s69, s69, 0
	s_add_i32 s70, s79, s13
	global_load_lds_dwordx4 v128, s[98:99] offset:128
	s_mov_b32 m0, s70
	ds_read_b128 v[198:201], v157 offset:53248
	global_load_lds_dwordx4 v132, s[68:69]
	s_add_i32 m0, s70, 0x2000
	ds_read_b128 v[202:205], v157 offset:54272
	global_load_lds_dwordx4 v128, s[68:69]
	s_add_i32 m0, s31, -128
	ds_read_b128 v[206:209], v157 offset:55296
	global_load_lds_dwordx4 v134, s[100:101] offset:128
	s_add_i32 m0, s33, -128
	ds_read_b128 v[210:213], v157 offset:56320
	global_load_lds_dwordx4 v130, s[100:101] offset:128
	s_waitcnt vmcnt(8) lgkmcnt(0)
	s_barrier
	v_mfma_i32_16x16x64_i8 v[60:63], v[144:147], v[182:185], v[60:63]
	v_mfma_i32_16x16x64_i8 v[52:55], v[158:161], v[182:185], v[52:55]
	v_mfma_i32_16x16x64_i8 v[44:47], v[144:147], v[190:193], v[44:47]
	v_mfma_i32_16x16x64_i8 v[36:39], v[158:161], v[190:193], v[36:39]
	v_mfma_i32_16x16x64_i8 v[28:31], v[144:147], v[198:201], v[28:31]
	v_mfma_i32_16x16x64_i8 v[20:23], v[158:161], v[198:201], v[20:23]
	v_mfma_i32_16x16x64_i8 v[12:15], v[144:147], v[206:209], v[12:15]
	v_mfma_i32_16x16x64_i8 v[4:7], v[158:161], v[206:209], v[4:7]
	v_mfma_i32_16x16x64_i8 v[60:63], v[148:151], v[186:189], v[60:63]
	v_mfma_i32_16x16x64_i8 v[52:55], v[162:165], v[186:189], v[52:55]
	v_mfma_i32_16x16x64_i8 v[44:47], v[148:151], v[194:197], v[44:47]
	v_mfma_i32_16x16x64_i8 v[36:39], v[162:165], v[194:197], v[36:39]
	v_mfma_i32_16x16x64_i8 v[28:31], v[148:151], v[202:205], v[28:31]
	v_mfma_i32_16x16x64_i8 v[20:23], v[162:165], v[202:205], v[20:23]
	v_mfma_i32_16x16x64_i8 v[12:15], v[148:151], v[210:213], v[12:15]
	v_mfma_i32_16x16x64_i8 v[4:7], v[162:165], v[210:213], v[4:7]
	v_mfma_i32_16x16x64_i8 v[56:59], v[166:169], v[182:185], v[56:59]
	v_mfma_i32_16x16x64_i8 v[48:51], v[174:177], v[182:185], v[48:51]
	v_mfma_i32_16x16x64_i8 v[40:43], v[166:169], v[190:193], v[40:43]
	v_mfma_i32_16x16x64_i8 v[32:35], v[174:177], v[190:193], v[32:35]
	v_mfma_i32_16x16x64_i8 v[24:27], v[166:169], v[198:201], v[24:27]
	v_mfma_i32_16x16x64_i8 v[16:19], v[174:177], v[198:201], v[16:19]
	v_mfma_i32_16x16x64_i8 v[8:11], v[166:169], v[206:209], v[8:11]
	v_mfma_i32_16x16x64_i8 v[0:3], v[174:177], v[206:209], v[0:3]
	v_mfma_i32_16x16x64_i8 v[56:59], v[170:173], v[186:189], v[56:59]
	v_mfma_i32_16x16x64_i8 v[48:51], v[178:181], v[186:189], v[48:51]
	v_mfma_i32_16x16x64_i8 v[40:43], v[170:173], v[194:197], v[40:43]
	v_mfma_i32_16x16x64_i8 v[32:35], v[178:181], v[194:197], v[32:35]
	v_mfma_i32_16x16x64_i8 v[24:27], v[170:173], v[202:205], v[24:27]
	v_mfma_i32_16x16x64_i8 v[16:19], v[178:181], v[202:205], v[16:19]
	v_mfma_i32_16x16x64_i8 v[8:11], v[170:173], v[210:213], v[8:11]
	v_mfma_i32_16x16x64_i8 v[0:3], v[178:181], v[210:213], v[0:3]
	s_barrier
	s_add_i32 s77, s77, 2
	s_add_u32 s66, s66, 0x100
	s_addc_u32 s67, s67, 0
	s_add_u32 s73, s73, 0x100
	s_addc_u32 s76, s76, 0
	s_cmp_gt_u32 s77, 29
	s_cbranch_scc0 .LBB0_173
	s_and_b64 vcc, exec, s[20:21]
	s_cbranch_vccz .LBB0_176
	s_barrier

.LBB0_258:
	ds_read_b128 v[152:155], v149
	ds_read_b128 v[156:159], v149 offset:1024
	ds_read_b128 v[160:163], v149 offset:2048
	ds_read_b128 v[164:167], v149 offset:3072
	ds_read_b128 v[168:171], v150
	ds_read_b128 v[172:175], v150 offset:1024
	ds_read_b128 v[176:179], v150 offset:2048
	ds_read_b128 v[180:183], v150 offset:3072
	s_add_u32 s36, s22, 0x100
	s_addc_u32 s37, s23, 0
	s_cmpk_eq_i32 s62, 0xa8
	s_cselect_b32 s57, s5, s37
	s_cselect_b32 s56, s4, s36
	s_cselect_b32 s41, s21, s61
	s_cselect_b32 s40, s20, s60
	s_add_i32 m0, s25, 0xc000
	ds_read_b128 v[184:187], v151
	ds_read_b128 v[188:191], v151 offset:1024
	ds_read_b128 v[192:195], v151 offset:2048
	ds_read_b128 v[196:199], v151 offset:3072
	ds_read_b128 v[200:203], v151 offset:4096
	ds_read_b128 v[204:207], v151 offset:5120
	ds_read_b128 v[208:211], v151 offset:6144
	global_load_lds_dwordx4 v136, s[22:23]
	s_add_i32 m0, s25, 0xe000
	ds_read_b128 v[212:215], v151 offset:7168
	global_load_lds_dwordx4 v138, s[22:23]
	s_waitcnt vmcnt(8) lgkmcnt(0)
	s_barrier
	v_mfma_f32_16x16x32_bf16 v[124:127], v[152:155], v[184:187], v[124:127]
	v_mfma_f32_16x16x32_bf16 v[120:123], v[160:163], v[184:187], v[120:123]
	v_mfma_f32_16x16x32_bf16 v[116:119], v[152:155], v[192:195], v[116:119]
	v_mfma_f32_16x16x32_bf16 v[108:111], v[160:163], v[192:195], v[108:111]
	v_mfma_f32_16x16x32_bf16 v[100:103], v[152:155], v[200:203], v[100:103]
	v_mfma_f32_16x16x32_bf16 v[92:95], v[160:163], v[200:203], v[92:95]
	v_mfma_f32_16x16x32_bf16 v[84:87], v[152:155], v[208:211], v[84:87]
	v_mfma_f32_16x16x32_bf16 v[76:79], v[160:163], v[208:211], v[76:79]
	v_mfma_f32_16x16x32_bf16 v[124:127], v[156:159], v[188:191], v[124:127]
	v_mfma_f32_16x16x32_bf16 v[120:123], v[164:167], v[188:191], v[120:123]
	v_mfma_f32_16x16x32_bf16 v[116:119], v[156:159], v[196:199], v[116:119]
	v_mfma_f32_16x16x32_bf16 v[108:111], v[164:167], v[196:199], v[108:111]
	v_mfma_f32_16x16x32_bf16 v[100:103], v[156:159], v[204:207], v[100:103]
	v_mfma_f32_16x16x32_bf16 v[92:95], v[164:167], v[204:207], v[92:95]
	v_mfma_f32_16x16x32_bf16 v[84:87], v[156:159], v[212:215], v[84:87]
	v_mfma_f32_16x16x32_bf16 v[76:79], v[164:167], v[212:215], v[76:79]
	v_mfma_f32_16x16x32_bf16 v[112:115], v[168:171], v[184:187], v[112:115]
	v_mfma_f32_16x16x32_bf16 v[104:107], v[176:179], v[184:187], v[104:107]
	v_mfma_f32_16x16x32_bf16 v[96:99], v[168:171], v[192:195], v[96:99]
	v_mfma_f32_16x16x32_bf16 v[88:91], v[176:179], v[192:195], v[88:91]
	v_mfma_f32_16x16x32_bf16 v[80:83], v[168:171], v[200:203], v[80:83]
	v_mfma_f32_16x16x32_bf16 v[72:75], v[176:179], v[200:203], v[72:75]
	v_mfma_f32_16x16x32_bf16 v[68:71], v[168:171], v[208:211], v[68:71]
	v_mfma_f32_16x16x32_bf16 v[64:67], v[176:179], v[208:211], v[64:67]
	v_mfma_f32_16x16x32_bf16 v[112:115], v[172:175], v[188:191], v[112:115]
	v_mfma_f32_16x16x32_bf16 v[104:107], v[180:183], v[188:191], v[104:107]
	v_mfma_f32_16x16x32_bf16 v[96:99], v[172:175], v[196:199], v[96:99]
	v_mfma_f32_16x16x32_bf16 v[88:91], v[180:183], v[196:199], v[88:91]
	v_mfma_f32_16x16x32_bf16 v[80:83], v[172:175], v[204:207], v[80:83]
	v_mfma_f32_16x16x32_bf16 v[72:75], v[180:183], v[204:207], v[72:75]
	v_mfma_f32_16x16x32_bf16 v[68:71], v[172:175], v[212:215], v[68:71]
	v_mfma_f32_16x16x32_bf16 v[64:67], v[180:183], v[212:215], v[64:67]
	s_barrier
	s_add_i32 s22, s35, s3
	s_mov_b32 m0, s22
	ds_read_b128 v[184:187], v151 offset:16384
	ds_read_b128 v[188:191], v151 offset:17408
	ds_read_b128 v[192:195], v151 offset:18432
	ds_read_b128 v[196:199], v151 offset:19456
	global_load_lds_dwordx4 v132, s[40:41]
	s_add_i32 m0, s22, 0x2000
	s_add_u32 s22, s40, 0x2b0000
	s_mov_b64 s[98:99], s[40:41]
	s_addc_u32 s23, s41, 0
	s_add_i32 s63, s52, s3
	global_load_lds_dwordx4 v128, s[98:99]
	s_mov_b32 m0, s63
	ds_read_b128 v[200:203], v151 offset:20480
	global_load_lds_dwordx4 v132, s[22:23]
	s_add_i32 m0, s63, 0x2000
	ds_read_b128 v[204:207], v151 offset:21504
	global_load_lds_dwordx4 v128, s[22:23]
	s_mov_b32 m0, s25
	ds_read_b128 v[208:211], v151 offset:22528
	global_load_lds_dwordx4 v134, s[56:57]
	s_mov_b32 m0, s26
	ds_read_b128 v[212:215], v151 offset:23552
	global_load_lds_dwordx4 v130, s[56:57]
	s_waitcnt vmcnt(8) lgkmcnt(0)
	s_barrier
	v_mfma_f32_16x16x32_bf16 v[60:63], v[152:155], v[184:187], v[60:63]
	v_mfma_f32_16x16x32_bf16 v[56:59], v[160:163], v[184:187], v[56:59]
	v_mfma_f32_16x16x32_bf16 v[52:55], v[152:155], v[192:195], v[52:55]
	v_mfma_f32_16x16x32_bf16 v[44:47], v[160:163], v[192:195], v[44:47]
	v_mfma_f32_16x16x32_bf16 v[36:39], v[152:155], v[200:203], v[36:39]
	v_mfma_f32_16x16x32_bf16 v[28:31], v[160:163], v[200:203], v[28:31]
	v_mfma_f32_16x16x32_bf16 v[20:23], v[152:155], v[208:211], v[20:23]
	v_mfma_f32_16x16x32_bf16 v[12:15], v[160:163], v[208:211], v[12:15]
	v_mfma_f32_16x16x32_bf16 v[60:63], v[156:159], v[188:191], v[60:63]
	v_mfma_f32_16x16x32_bf16 v[56:59], v[164:167], v[188:191], v[56:59]
	v_mfma_f32_16x16x32_bf16 v[52:55], v[156:159], v[196:199], v[52:55]
	v_mfma_f32_16x16x32_bf16 v[44:47], v[164:167], v[196:199], v[44:47]
	v_mfma_f32_16x16x32_bf16 v[36:39], v[156:159], v[204:207], v[36:39]
	v_mfma_f32_16x16x32_bf16 v[28:31], v[164:167], v[204:207], v[28:31]
	v_mfma_f32_16x16x32_bf16 v[20:23], v[156:159], v[212:215], v[20:23]
	v_mfma_f32_16x16x32_bf16 v[12:15], v[164:167], v[212:215], v[12:15]
	v_mfma_f32_16x16x32_bf16 v[48:51], v[168:171], v[184:187], v[48:51]
	v_mfma_f32_16x16x32_bf16 v[40:43], v[176:179], v[184:187], v[40:43]
	v_mfma_f32_16x16x32_bf16 v[32:35], v[168:171], v[192:195], v[32:35]
	v_mfma_f32_16x16x32_bf16 v[24:27], v[176:179], v[192:195], v[24:27]
	v_mfma_f32_16x16x32_bf16 v[16:19], v[168:171], v[200:203], v[16:19]
	v_mfma_f32_16x16x32_bf16 v[8:11], v[176:179], v[200:203], v[8:11]
	v_mfma_f32_16x16x32_bf16 v[4:7], v[168:171], v[208:211], v[4:7]
	v_mfma_f32_16x16x32_bf16 v[0:3], v[176:179], v[208:211], v[0:3]
	v_mfma_f32_16x16x32_bf16 v[48:51], v[172:175], v[188:191], v[48:51]
	v_mfma_f32_16x16x32_bf16 v[40:43], v[180:183], v[188:191], v[40:43]
	v_mfma_f32_16x16x32_bf16 v[32:35], v[172:175], v[196:199], v[32:35]
	v_mfma_f32_16x16x32_bf16 v[24:27], v[180:183], v[196:199], v[24:27]
	v_mfma_f32_16x16x32_bf16 v[16:19], v[172:175], v[204:207], v[16:19]
	v_mfma_f32_16x16x32_bf16 v[8:11], v[180:183], v[204:207], v[8:11]
	v_mfma_f32_16x16x32_bf16 v[4:7], v[172:175], v[212:215], v[4:7]
	v_mfma_f32_16x16x32_bf16 v[0:3], v[180:183], v[212:215], v[0:3]
	s_barrier
	s_add_i32 s63, 0, 0x18000
	s_add_i32 s64, 0, 0x1c000
	ds_read_b128 v[152:155], v149 offset:32768
	ds_read_b128 v[156:159], v149 offset:33792
	ds_read_b128 v[160:163], v149 offset:34816
	ds_read_b128 v[164:167], v149 offset:35840
	ds_read_b128 v[168:171], v150 offset:32768
	ds_read_b128 v[172:175], v150 offset:33792
	ds_read_b128 v[176:179], v150 offset:34816
	ds_read_b128 v[180:183], v150 offset:35840
	s_add_u32 s22, s56, 0x2b0000
	s_addc_u32 s23, s57, 0
	s_mov_b32 m0, s27
	ds_read_b128 v[184:187], v151 offset:32768
	ds_read_b128 v[188:191], v151 offset:33792
	ds_read_b128 v[192:195], v151 offset:34816
	ds_read_b128 v[196:199], v151 offset:35840
	ds_read_b128 v[200:203], v151 offset:36864
	ds_read_b128 v[204:207], v151 offset:37888
	ds_read_b128 v[208:211], v151 offset:38912
	global_load_lds_dwordx4 v134, s[22:23]
	s_mov_b32 m0, s28
	ds_read_b128 v[212:215], v151 offset:39936
	global_load_lds_dwordx4 v130, s[22:23]
	s_waitcnt vmcnt(8) lgkmcnt(0)
	s_barrier
	v_mfma_f32_16x16x32_bf16 v[124:127], v[152:155], v[184:187], v[124:127]
	v_mfma_f32_16x16x32_bf16 v[120:123], v[160:163], v[184:187], v[120:123]
	v_mfma_f32_16x16x32_bf16 v[116:119], v[152:155], v[192:195], v[116:119]
	v_mfma_f32_16x16x32_bf16 v[108:111], v[160:163], v[192:195], v[108:111]
	v_mfma_f32_16x16x32_bf16 v[100:103], v[152:155], v[200:203], v[100:103]
	v_mfma_f32_16x16x32_bf16 v[92:95], v[160:163], v[200:203], v[92:95]
	v_mfma_f32_16x16x32_bf16 v[84:87], v[152:155], v[208:211], v[84:87]
	v_mfma_f32_16x16x32_bf16 v[76:79], v[160:163], v[208:211], v[76:79]
	v_mfma_f32_16x16x32_bf16 v[124:127], v[156:159], v[188:191], v[124:127]
	v_mfma_f32_16x16x32_bf16 v[120:123], v[164:167], v[188:191], v[120:123]
	v_mfma_f32_16x16x32_bf16 v[116:119], v[156:159], v[196:199], v[116:119]
	v_mfma_f32_16x16x32_bf16 v[108:111], v[164:167], v[196:199], v[108:111]
	v_mfma_f32_16x16x32_bf16 v[100:103], v[156:159], v[204:207], v[100:103]
	v_mfma_f32_16x16x32_bf16 v[92:95], v[164:167], v[204:207], v[92:95]
	v_mfma_f32_16x16x32_bf16 v[84:87], v[156:159], v[212:215], v[84:87]
	v_mfma_f32_16x16x32_bf16 v[76:79], v[164:167], v[212:215], v[76:79]
	v_mfma_f32_16x16x32_bf16 v[112:115], v[168:171], v[184:187], v[112:115]
	v_mfma_f32_16x16x32_bf16 v[104:107], v[176:179], v[184:187], v[104:107]
	v_mfma_f32_16x16x32_bf16 v[96:99], v[168:171], v[192:195], v[96:99]
	v_mfma_f32_16x16x32_bf16 v[88:91], v[176:179], v[192:195], v[88:91]
	v_mfma_f32_16x16x32_bf16 v[80:83], v[168:171], v[200:203], v[80:83]
	v_mfma_f32_16x16x32_bf16 v[72:75], v[176:179], v[200:203], v[72:75]
	v_mfma_f32_16x16x32_bf16 v[68:71], v[168:171], v[208:211], v[68:71]
	v_mfma_f32_16x16x32_bf16 v[64:67], v[176:179], v[208:211], v[64:67]
	v_mfma_f32_16x16x32_bf16 v[112:115], v[172:175], v[188:191], v[112:115]
	v_mfma_f32_16x16x32_bf16 v[104:107], v[180:183], v[188:191], v[104:107]
	v_mfma_f32_16x16x32_bf16 v[96:99], v[172:175], v[196:199], v[96:99]
	v_mfma_f32_16x16x32_bf16 v[88:91], v[180:183], v[196:199], v[88:91]
	v_mfma_f32_16x16x32_bf16 v[80:83], v[172:175], v[204:207], v[80:83]
	v_mfma_f32_16x16x32_bf16 v[72:75], v[180:183], v[204:207], v[72:75]
	v_mfma_f32_16x16x32_bf16 v[68:71], v[172:175], v[212:215], v[68:71]
	v_mfma_f32_16x16x32_bf16 v[64:67], v[180:183], v[212:215], v[64:67]
	s_barrier
	s_add_i32 s22, s63, s3
	s_add_i32 m0, s22, -128
	ds_read_b128 v[184:187], v151 offset:49152
	ds_read_b128 v[188:191], v151 offset:50176
	ds_read_b128 v[192:195], v151 offset:51200
	ds_read_b128 v[196:199], v151 offset:52224
	global_load_lds_dwordx4 v132, s[40:41] offset:128
	s_add_i32 m0, s22, 8064
	s_add_u32 s22, s40, 0x2b0080
	s_addc_u32 s23, s41, 0
	s_add_i32 s40, s64, s3
	global_load_lds_dwordx4 v128, s[98:99] offset:128
	s_mov_b32 m0, s40
	ds_read_b128 v[200:203], v151 offset:53248
	global_load_lds_dwordx4 v132, s[22:23]
	s_add_i32 m0, s40, 0x2000
	ds_read_b128 v[204:207], v151 offset:54272
	global_load_lds_dwordx4 v128, s[22:23]
	s_add_i32 m0, s31, -128
	ds_read_b128 v[208:211], v151 offset:55296
	global_load_lds_dwordx4 v134, s[56:57] offset:128
	s_add_i32 m0, s33, -128
	ds_read_b128 v[212:215], v151 offset:56320
	global_load_lds_dwordx4 v130, s[56:57] offset:128
	s_waitcnt vmcnt(8) lgkmcnt(0)
	s_barrier
	v_mfma_f32_16x16x32_bf16 v[60:63], v[152:155], v[184:187], v[60:63]
	v_mfma_f32_16x16x32_bf16 v[56:59], v[160:163], v[184:187], v[56:59]
	v_mfma_f32_16x16x32_bf16 v[52:55], v[152:155], v[192:195], v[52:55]
	v_mfma_f32_16x16x32_bf16 v[44:47], v[160:163], v[192:195], v[44:47]
	v_mfma_f32_16x16x32_bf16 v[36:39], v[152:155], v[200:203], v[36:39]
	v_mfma_f32_16x16x32_bf16 v[28:31], v[160:163], v[200:203], v[28:31]
	v_mfma_f32_16x16x32_bf16 v[20:23], v[152:155], v[208:211], v[20:23]
	v_mfma_f32_16x16x32_bf16 v[12:15], v[160:163], v[208:211], v[12:15]
	v_mfma_f32_16x16x32_bf16 v[60:63], v[156:159], v[188:191], v[60:63]
	v_mfma_f32_16x16x32_bf16 v[56:59], v[164:167], v[188:191], v[56:59]
	v_mfma_f32_16x16x32_bf16 v[52:55], v[156:159], v[196:199], v[52:55]
	v_mfma_f32_16x16x32_bf16 v[44:47], v[164:167], v[196:199], v[44:47]
	v_mfma_f32_16x16x32_bf16 v[36:39], v[156:159], v[204:207], v[36:39]
	v_mfma_f32_16x16x32_bf16 v[28:31], v[164:167], v[204:207], v[28:31]
	v_mfma_f32_16x16x32_bf16 v[20:23], v[156:159], v[212:215], v[20:23]
	v_mfma_f32_16x16x32_bf16 v[12:15], v[164:167], v[212:215], v[12:15]
	v_mfma_f32_16x16x32_bf16 v[48:51], v[168:171], v[184:187], v[48:51]
	v_mfma_f32_16x16x32_bf16 v[40:43], v[176:179], v[184:187], v[40:43]
	v_mfma_f32_16x16x32_bf16 v[32:35], v[168:171], v[192:195], v[32:35]
	v_mfma_f32_16x16x32_bf16 v[24:27], v[176:179], v[192:195], v[24:27]
	v_mfma_f32_16x16x32_bf16 v[16:19], v[168:171], v[200:203], v[16:19]
	v_mfma_f32_16x16x32_bf16 v[8:11], v[176:179], v[200:203], v[8:11]
	v_mfma_f32_16x16x32_bf16 v[4:7], v[168:171], v[208:211], v[4:7]
	v_mfma_f32_16x16x32_bf16 v[0:3], v[176:179], v[208:211], v[0:3]
	v_mfma_f32_16x16x32_bf16 v[48:51], v[172:175], v[188:191], v[48:51]
	v_mfma_f32_16x16x32_bf16 v[40:43], v[180:183], v[188:191], v[40:43]
	v_mfma_f32_16x16x32_bf16 v[32:35], v[172:175], v[196:199], v[32:35]
	v_mfma_f32_16x16x32_bf16 v[24:27], v[180:183], v[196:199], v[24:27]
	v_mfma_f32_16x16x32_bf16 v[16:19], v[172:175], v[204:207], v[16:19]
	v_mfma_f32_16x16x32_bf16 v[8:11], v[180:183], v[204:207], v[8:11]
	v_mfma_f32_16x16x32_bf16 v[4:7], v[172:175], v[212:215], v[4:7]
	v_mfma_f32_16x16x32_bf16 v[0:3], v[180:183], v[212:215], v[0:3]
	s_barrier
	s_add_i32 s62, s62, 2
	s_add_u32 s60, s60, 0x100
	s_addc_u32 s61, s61, 0
	s_cmpk_gt_u32 s62, 0xa9
	s_mov_b64 s[22:23], s[36:37]
	s_cbranch_scc0 .LBB0_258
	s_and_b64 vcc, exec, s[14:15]
	s_cbranch_vccz .LBB0_261
	s_barrier

.LBB0_394:
	ds_read_b128 v[156:159], v152
	ds_read_b128 v[160:163], v152 offset:1024
	ds_read_b128 v[164:167], v152 offset:2048
	ds_read_b128 v[168:171], v152 offset:3072
	ds_read_b128 v[172:175], v153
	ds_read_b128 v[176:179], v153 offset:1024
	ds_read_b128 v[180:183], v153 offset:2048
	ds_read_b128 v[184:187], v153 offset:3072
	s_add_u32 s40, s38, 0xfff00080
	s_addc_u32 s41, s39, -1
	s_cmp_eq_u32 s64, 60
	s_cselect_b32 s57, s21, s41
	s_cselect_b32 s56, s60, s40
	s_cselect_b32 s41, s15, s63
	s_cselect_b32 s40, s61, s62
	s_add_i32 m0, s29, 0xc000
	ds_read_b128 v[188:191], v154
	ds_read_b128 v[192:195], v154 offset:1024
	ds_read_b128 v[196:199], v154 offset:2048
	ds_read_b128 v[200:203], v154 offset:3072
	ds_read_b128 v[204:207], v154 offset:4096
	ds_read_b128 v[208:211], v154 offset:5120
	ds_read_b128 v[212:215], v154 offset:6144
	global_load_lds_dwordx4 v140, s[38:39]
	s_add_i32 m0, s29, 0xe000
	ds_read_b128 v[216:219], v154 offset:7168
	global_load_lds_dwordx4 v142, s[38:39]
	s_waitcnt vmcnt(8) lgkmcnt(0)
	s_barrier
	v_mfma_f32_16x16x32_bf16 v[124:127], v[156:159], v[188:191], v[124:127]
	v_mfma_f32_16x16x32_bf16 v[120:123], v[164:167], v[188:191], v[120:123]
	v_mfma_f32_16x16x32_bf16 v[112:115], v[156:159], v[196:199], v[112:115]
	v_mfma_f32_16x16x32_bf16 v[104:107], v[164:167], v[196:199], v[104:107]
	v_mfma_f32_16x16x32_bf16 v[96:99], v[156:159], v[204:207], v[96:99]
	v_mfma_f32_16x16x32_bf16 v[88:91], v[164:167], v[204:207], v[88:91]
	v_mfma_f32_16x16x32_bf16 v[80:83], v[156:159], v[212:215], v[80:83]
	v_mfma_f32_16x16x32_bf16 v[72:75], v[164:167], v[212:215], v[72:75]
	v_mfma_f32_16x16x32_bf16 v[124:127], v[160:163], v[192:195], v[124:127]
	v_mfma_f32_16x16x32_bf16 v[120:123], v[168:171], v[192:195], v[120:123]
	v_mfma_f32_16x16x32_bf16 v[112:115], v[160:163], v[200:203], v[112:115]
	v_mfma_f32_16x16x32_bf16 v[104:107], v[168:171], v[200:203], v[104:107]
	v_mfma_f32_16x16x32_bf16 v[96:99], v[160:163], v[208:211], v[96:99]
	v_mfma_f32_16x16x32_bf16 v[88:91], v[168:171], v[208:211], v[88:91]
	v_mfma_f32_16x16x32_bf16 v[80:83], v[160:163], v[216:219], v[80:83]
	v_mfma_f32_16x16x32_bf16 v[72:75], v[168:171], v[216:219], v[72:75]
	v_mfma_f32_16x16x32_bf16 v[116:119], v[172:175], v[188:191], v[116:119]
	v_mfma_f32_16x16x32_bf16 v[108:111], v[180:183], v[188:191], v[108:111]
	v_mfma_f32_16x16x32_bf16 v[100:103], v[172:175], v[196:199], v[100:103]
	v_mfma_f32_16x16x32_bf16 v[92:95], v[180:183], v[196:199], v[92:95]
	v_mfma_f32_16x16x32_bf16 v[84:87], v[172:175], v[204:207], v[84:87]
	v_mfma_f32_16x16x32_bf16 v[76:79], v[180:183], v[204:207], v[76:79]
	v_mfma_f32_16x16x32_bf16 v[68:71], v[172:175], v[212:215], v[68:71]
	v_mfma_f32_16x16x32_bf16 v[64:67], v[180:183], v[212:215], v[64:67]
	v_mfma_f32_16x16x32_bf16 v[116:119], v[176:179], v[192:195], v[116:119]
	v_mfma_f32_16x16x32_bf16 v[108:111], v[184:187], v[192:195], v[108:111]
	v_mfma_f32_16x16x32_bf16 v[100:103], v[176:179], v[200:203], v[100:103]
	v_mfma_f32_16x16x32_bf16 v[92:95], v[184:187], v[200:203], v[92:95]
	v_mfma_f32_16x16x32_bf16 v[84:87], v[176:179], v[208:211], v[84:87]
	v_mfma_f32_16x16x32_bf16 v[76:79], v[184:187], v[208:211], v[76:79]
	v_mfma_f32_16x16x32_bf16 v[68:71], v[176:179], v[216:219], v[68:71]
	v_mfma_f32_16x16x32_bf16 v[64:67], v[184:187], v[216:219], v[64:67]
	s_barrier
	s_add_i32 s65, s58, s24
	s_mov_b32 m0, s65
	ds_read_b128 v[188:191], v154 offset:16384
	ds_read_b128 v[192:195], v154 offset:17408
	ds_read_b128 v[196:199], v154 offset:18432
	ds_read_b128 v[200:203], v154 offset:19456
	ds_read_b128 v[204:207], v154 offset:20480
	global_load_lds_dwordx4 v132, s[40:41]
	s_add_i32 m0, s65, 0x2000
	s_add_u32 s66, s40, 0x100000
	s_mov_b64 s[98:99], s[40:41]
	s_addc_u32 s67, s41, 0
	s_add_i32 s65, s59, s24
	global_load_lds_dwordx4 v128, s[98:99]
	s_mov_b32 m0, s65
	s_mov_b64 s[100:101], s[56:57]
	global_load_lds_dwordx4 v132, s[66:67]
	s_add_i32 m0, s65, 0x2000
	ds_read_b128 v[208:211], v154 offset:21504
	global_load_lds_dwordx4 v128, s[66:67]
	s_mov_b32 m0, s29
	ds_read_b128 v[212:215], v154 offset:22528
	global_load_lds_dwordx4 v134, s[100:101]
	s_mov_b32 m0, s30
	ds_read_b128 v[216:219], v154 offset:23552
	global_load_lds_dwordx4 v130, s[100:101]
	s_waitcnt vmcnt(8) lgkmcnt(0)
	s_barrier
	v_mfma_f32_16x16x32_bf16 v[60:63], v[156:159], v[188:191], v[60:63]
	v_mfma_f32_16x16x32_bf16 v[56:59], v[164:167], v[188:191], v[56:59]
	v_mfma_f32_16x16x32_bf16 v[52:55], v[156:159], v[196:199], v[52:55]
	v_mfma_f32_16x16x32_bf16 v[44:47], v[164:167], v[196:199], v[44:47]
	v_mfma_f32_16x16x32_bf16 v[36:39], v[156:159], v[204:207], v[36:39]
	v_mfma_f32_16x16x32_bf16 v[28:31], v[164:167], v[204:207], v[28:31]
	v_mfma_f32_16x16x32_bf16 v[20:23], v[156:159], v[212:215], v[20:23]
	v_mfma_f32_16x16x32_bf16 v[12:15], v[164:167], v[212:215], v[12:15]
	v_mfma_f32_16x16x32_bf16 v[60:63], v[160:163], v[192:195], v[60:63]
	v_mfma_f32_16x16x32_bf16 v[56:59], v[168:171], v[192:195], v[56:59]
	v_mfma_f32_16x16x32_bf16 v[52:55], v[160:163], v[200:203], v[52:55]
	v_mfma_f32_16x16x32_bf16 v[44:47], v[168:171], v[200:203], v[44:47]
	v_mfma_f32_16x16x32_bf16 v[36:39], v[160:163], v[208:211], v[36:39]
	v_mfma_f32_16x16x32_bf16 v[28:31], v[168:171], v[208:211], v[28:31]
	v_mfma_f32_16x16x32_bf16 v[20:23], v[160:163], v[216:219], v[20:23]
	v_mfma_f32_16x16x32_bf16 v[12:15], v[168:171], v[216:219], v[12:15]
	v_mfma_f32_16x16x32_bf16 v[48:51], v[172:175], v[188:191], v[48:51]
	v_mfma_f32_16x16x32_bf16 v[40:43], v[180:183], v[188:191], v[40:43]
	v_mfma_f32_16x16x32_bf16 v[32:35], v[172:175], v[196:199], v[32:35]
	v_mfma_f32_16x16x32_bf16 v[24:27], v[180:183], v[196:199], v[24:27]
	v_mfma_f32_16x16x32_bf16 v[16:19], v[172:175], v[204:207], v[16:19]
	v_mfma_f32_16x16x32_bf16 v[8:11], v[180:183], v[204:207], v[8:11]
	v_mfma_f32_16x16x32_bf16 v[4:7], v[172:175], v[212:215], v[4:7]
	v_mfma_f32_16x16x32_bf16 v[0:3], v[180:183], v[212:215], v[0:3]
	v_mfma_f32_16x16x32_bf16 v[48:51], v[176:179], v[192:195], v[48:51]
	v_mfma_f32_16x16x32_bf16 v[40:43], v[184:187], v[192:195], v[40:43]
	v_mfma_f32_16x16x32_bf16 v[32:35], v[176:179], v[200:203], v[32:35]
	v_mfma_f32_16x16x32_bf16 v[24:27], v[184:187], v[200:203], v[24:27]
	v_mfma_f32_16x16x32_bf16 v[16:19], v[176:179], v[208:211], v[16:19]
	v_mfma_f32_16x16x32_bf16 v[8:11], v[184:187], v[208:211], v[8:11]
	v_mfma_f32_16x16x32_bf16 v[4:7], v[176:179], v[216:219], v[4:7]
	v_mfma_f32_16x16x32_bf16 v[0:3], v[184:187], v[216:219], v[0:3]
	s_barrier
	s_add_i32 s65, 0, 0x18000
	s_add_i32 s66, 0, 0x1c000
	ds_read_b128 v[156:159], v152 offset:32768
	ds_read_b128 v[160:163], v152 offset:33792
	ds_read_b128 v[164:167], v152 offset:34816
	ds_read_b128 v[168:171], v152 offset:35840
	ds_read_b128 v[172:175], v153 offset:32768
	ds_read_b128 v[176:179], v153 offset:33792
	ds_read_b128 v[180:183], v153 offset:34816
	ds_read_b128 v[184:187], v153 offset:35840
	s_add_u32 s56, s56, 0x100000
	s_addc_u32 s57, s57, 0
	s_mov_b32 m0, s31
	ds_read_b128 v[188:191], v154 offset:32768
	ds_read_b128 v[192:195], v154 offset:33792
	ds_read_b128 v[196:199], v154 offset:34816
	ds_read_b128 v[200:203], v154 offset:35840
	ds_read_b128 v[204:207], v154 offset:36864
	ds_read_b128 v[208:211], v154 offset:37888
	ds_read_b128 v[212:215], v154 offset:38912
	global_load_lds_dwordx4 v134, s[56:57]
	s_mov_b32 m0, s33
	ds_read_b128 v[216:219], v154 offset:39936
	global_load_lds_dwordx4 v130, s[56:57]
	s_waitcnt vmcnt(8) lgkmcnt(0)
	s_barrier
	v_mfma_f32_16x16x32_bf16 v[124:127], v[156:159], v[188:191], v[124:127]
	v_mfma_f32_16x16x32_bf16 v[120:123], v[164:167], v[188:191], v[120:123]
	v_mfma_f32_16x16x32_bf16 v[112:115], v[156:159], v[196:199], v[112:115]
	v_mfma_f32_16x16x32_bf16 v[104:107], v[164:167], v[196:199], v[104:107]
	v_mfma_f32_16x16x32_bf16 v[96:99], v[156:159], v[204:207], v[96:99]
	v_mfma_f32_16x16x32_bf16 v[88:91], v[164:167], v[204:207], v[88:91]
	v_mfma_f32_16x16x32_bf16 v[80:83], v[156:159], v[212:215], v[80:83]
	v_mfma_f32_16x16x32_bf16 v[72:75], v[164:167], v[212:215], v[72:75]
	v_mfma_f32_16x16x32_bf16 v[124:127], v[160:163], v[192:195], v[124:127]
	v_mfma_f32_16x16x32_bf16 v[120:123], v[168:171], v[192:195], v[120:123]
	v_mfma_f32_16x16x32_bf16 v[112:115], v[160:163], v[200:203], v[112:115]
	v_mfma_f32_16x16x32_bf16 v[104:107], v[168:171], v[200:203], v[104:107]
	v_mfma_f32_16x16x32_bf16 v[96:99], v[160:163], v[208:211], v[96:99]
	v_mfma_f32_16x16x32_bf16 v[88:91], v[168:171], v[208:211], v[88:91]
	v_mfma_f32_16x16x32_bf16 v[80:83], v[160:163], v[216:219], v[80:83]
	v_mfma_f32_16x16x32_bf16 v[72:75], v[168:171], v[216:219], v[72:75]
	v_mfma_f32_16x16x32_bf16 v[116:119], v[172:175], v[188:191], v[116:119]
	v_mfma_f32_16x16x32_bf16 v[108:111], v[180:183], v[188:191], v[108:111]
	v_mfma_f32_16x16x32_bf16 v[100:103], v[172:175], v[196:199], v[100:103]
	v_mfma_f32_16x16x32_bf16 v[92:95], v[180:183], v[196:199], v[92:95]
	v_mfma_f32_16x16x32_bf16 v[84:87], v[172:175], v[204:207], v[84:87]
	v_mfma_f32_16x16x32_bf16 v[76:79], v[180:183], v[204:207], v[76:79]
	v_mfma_f32_16x16x32_bf16 v[68:71], v[172:175], v[212:215], v[68:71]
	v_mfma_f32_16x16x32_bf16 v[64:67], v[180:183], v[212:215], v[64:67]
	v_mfma_f32_16x16x32_bf16 v[116:119], v[176:179], v[192:195], v[116:119]
	v_mfma_f32_16x16x32_bf16 v[108:111], v[184:187], v[192:195], v[108:111]
	v_mfma_f32_16x16x32_bf16 v[100:103], v[176:179], v[200:203], v[100:103]
	v_mfma_f32_16x16x32_bf16 v[92:95], v[184:187], v[200:203], v[92:95]
	v_mfma_f32_16x16x32_bf16 v[84:87], v[176:179], v[208:211], v[84:87]
	v_mfma_f32_16x16x32_bf16 v[76:79], v[184:187], v[208:211], v[76:79]
	v_mfma_f32_16x16x32_bf16 v[68:71], v[176:179], v[216:219], v[68:71]
	v_mfma_f32_16x16x32_bf16 v[64:67], v[184:187], v[216:219], v[64:67]
	s_barrier
	s_add_i32 s56, s65, s24
	s_add_i32 m0, s56, -128
	ds_read_b128 v[188:191], v154 offset:49152
	ds_read_b128 v[192:195], v154 offset:50176
	ds_read_b128 v[196:199], v154 offset:51200
	ds_read_b128 v[200:203], v154 offset:52224
	global_load_lds_dwordx4 v132, s[40:41] offset:128
	s_add_i32 m0, s56, 8064
	s_add_u32 s40, s40, 0x100080
	s_addc_u32 s41, s41, 0
	s_add_i32 s56, s66, s24
	global_load_lds_dwordx4 v128, s[98:99] offset:128
	s_mov_b32 m0, s56
	ds_read_b128 v[204:207], v154 offset:53248
	global_load_lds_dwordx4 v132, s[40:41]
	s_add_i32 m0, s56, 0x2000
	ds_read_b128 v[208:211], v154 offset:54272
	global_load_lds_dwordx4 v128, s[40:41]
	s_add_i32 m0, s54, -128
	ds_read_b128 v[212:215], v154 offset:55296
	global_load_lds_dwordx4 v134, s[100:101] offset:128
	s_add_i32 m0, s55, -128
	ds_read_b128 v[216:219], v154 offset:56320
	global_load_lds_dwordx4 v130, s[100:101] offset:128
	s_waitcnt vmcnt(8) lgkmcnt(0)
	s_barrier
	v_mfma_f32_16x16x32_bf16 v[60:63], v[156:159], v[188:191], v[60:63]
	v_mfma_f32_16x16x32_bf16 v[56:59], v[164:167], v[188:191], v[56:59]
	v_mfma_f32_16x16x32_bf16 v[52:55], v[156:159], v[196:199], v[52:55]
	v_mfma_f32_16x16x32_bf16 v[44:47], v[164:167], v[196:199], v[44:47]
	v_mfma_f32_16x16x32_bf16 v[36:39], v[156:159], v[204:207], v[36:39]
	v_mfma_f32_16x16x32_bf16 v[28:31], v[164:167], v[204:207], v[28:31]
	v_mfma_f32_16x16x32_bf16 v[20:23], v[156:159], v[212:215], v[20:23]
	v_mfma_f32_16x16x32_bf16 v[12:15], v[164:167], v[212:215], v[12:15]
	v_mfma_f32_16x16x32_bf16 v[60:63], v[160:163], v[192:195], v[60:63]
	v_mfma_f32_16x16x32_bf16 v[56:59], v[168:171], v[192:195], v[56:59]
	v_mfma_f32_16x16x32_bf16 v[52:55], v[160:163], v[200:203], v[52:55]
	v_mfma_f32_16x16x32_bf16 v[44:47], v[168:171], v[200:203], v[44:47]
	v_mfma_f32_16x16x32_bf16 v[36:39], v[160:163], v[208:211], v[36:39]
	v_mfma_f32_16x16x32_bf16 v[28:31], v[168:171], v[208:211], v[28:31]
	v_mfma_f32_16x16x32_bf16 v[20:23], v[160:163], v[216:219], v[20:23]
	v_mfma_f32_16x16x32_bf16 v[12:15], v[168:171], v[216:219], v[12:15]
	v_mfma_f32_16x16x32_bf16 v[48:51], v[172:175], v[188:191], v[48:51]
	v_mfma_f32_16x16x32_bf16 v[40:43], v[180:183], v[188:191], v[40:43]
	v_mfma_f32_16x16x32_bf16 v[32:35], v[172:175], v[196:199], v[32:35]
	v_mfma_f32_16x16x32_bf16 v[24:27], v[180:183], v[196:199], v[24:27]
	v_mfma_f32_16x16x32_bf16 v[16:19], v[172:175], v[204:207], v[16:19]
	v_mfma_f32_16x16x32_bf16 v[8:11], v[180:183], v[204:207], v[8:11]
	v_mfma_f32_16x16x32_bf16 v[4:7], v[172:175], v[212:215], v[4:7]
	v_mfma_f32_16x16x32_bf16 v[0:3], v[180:183], v[212:215], v[0:3]
	v_mfma_f32_16x16x32_bf16 v[48:51], v[176:179], v[192:195], v[48:51]
	v_mfma_f32_16x16x32_bf16 v[40:43], v[184:187], v[192:195], v[40:43]
	v_mfma_f32_16x16x32_bf16 v[32:35], v[176:179], v[200:203], v[32:35]
	v_mfma_f32_16x16x32_bf16 v[24:27], v[184:187], v[200:203], v[24:27]
	v_mfma_f32_16x16x32_bf16 v[16:19], v[176:179], v[208:211], v[16:19]
	v_mfma_f32_16x16x32_bf16 v[8:11], v[184:187], v[208:211], v[8:11]
	v_mfma_f32_16x16x32_bf16 v[4:7], v[176:179], v[216:219], v[4:7]
	v_mfma_f32_16x16x32_bf16 v[0:3], v[184:187], v[216:219], v[0:3]
	s_barrier
	s_add_i32 s64, s64, 2
	s_add_u32 s38, s38, 0x100
	s_addc_u32 s39, s39, 0
	s_add_u32 s62, s62, 0x100
	s_addc_u32 s63, s63, 0
	s_cmp_gt_u32 s64, 61
	s_cbranch_scc0 .LBB0_394
	s_and_b64 vcc, exec, s[12:13]
	s_cbranch_vccz .LBB0_397
	s_barrier

.LBB0_622:
	ds_read_b128 v[152:155], v149
	ds_read_b128 v[156:159], v149 offset:1024
	ds_read_b128 v[160:163], v149 offset:2048
	ds_read_b128 v[164:167], v149 offset:3072
	ds_read_b128 v[168:171], v150
	ds_read_b128 v[172:175], v150 offset:1024
	ds_read_b128 v[176:179], v150 offset:2048
	ds_read_b128 v[180:183], v150 offset:3072
	s_add_u32 s42, s40, 0xfff00080
	s_addc_u32 s43, s41, -1
	s_cmp_eq_u32 s61, 60
	s_cselect_b32 s45, s25, s43
	s_cselect_b32 s44, s57, s42
	s_cselect_b32 s43, s23, s60
	s_cselect_b32 s42, s58, s59
	s_add_i32 m0, s31, 0xc000
	ds_read_b128 v[184:187], v151
	ds_read_b128 v[188:191], v151 offset:1024
	ds_read_b128 v[192:195], v151 offset:2048
	ds_read_b128 v[196:199], v151 offset:3072
	ds_read_b128 v[200:203], v151 offset:4096
	ds_read_b128 v[204:207], v151 offset:5120
	ds_read_b128 v[208:211], v151 offset:6144
	global_load_lds_dwordx4 v136, s[40:41]
	s_add_i32 m0, s31, 0xe000
	ds_read_b128 v[212:215], v151 offset:7168
	global_load_lds_dwordx4 v138, s[40:41]
	s_waitcnt vmcnt(8) lgkmcnt(0)
	s_barrier
	v_mfma_f32_16x16x32_bf16 v[124:127], v[152:155], v[184:187], v[124:127]
	v_mfma_f32_16x16x32_bf16 v[120:123], v[160:163], v[184:187], v[120:123]
	v_mfma_f32_16x16x32_bf16 v[116:119], v[152:155], v[192:195], v[116:119]
	v_mfma_f32_16x16x32_bf16 v[108:111], v[160:163], v[192:195], v[108:111]
	v_mfma_f32_16x16x32_bf16 v[100:103], v[152:155], v[200:203], v[100:103]
	v_mfma_f32_16x16x32_bf16 v[92:95], v[160:163], v[200:203], v[92:95]
	v_mfma_f32_16x16x32_bf16 v[84:87], v[152:155], v[208:211], v[84:87]
	v_mfma_f32_16x16x32_bf16 v[76:79], v[160:163], v[208:211], v[76:79]
	v_mfma_f32_16x16x32_bf16 v[124:127], v[156:159], v[188:191], v[124:127]
	v_mfma_f32_16x16x32_bf16 v[120:123], v[164:167], v[188:191], v[120:123]
	v_mfma_f32_16x16x32_bf16 v[116:119], v[156:159], v[196:199], v[116:119]
	v_mfma_f32_16x16x32_bf16 v[108:111], v[164:167], v[196:199], v[108:111]
	v_mfma_f32_16x16x32_bf16 v[100:103], v[156:159], v[204:207], v[100:103]
	v_mfma_f32_16x16x32_bf16 v[92:95], v[164:167], v[204:207], v[92:95]
	v_mfma_f32_16x16x32_bf16 v[84:87], v[156:159], v[212:215], v[84:87]
	v_mfma_f32_16x16x32_bf16 v[76:79], v[164:167], v[212:215], v[76:79]
	v_mfma_f32_16x16x32_bf16 v[112:115], v[168:171], v[184:187], v[112:115]
	v_mfma_f32_16x16x32_bf16 v[104:107], v[176:179], v[184:187], v[104:107]
	v_mfma_f32_16x16x32_bf16 v[96:99], v[168:171], v[192:195], v[96:99]
	v_mfma_f32_16x16x32_bf16 v[88:91], v[176:179], v[192:195], v[88:91]
	v_mfma_f32_16x16x32_bf16 v[80:83], v[168:171], v[200:203], v[80:83]
	v_mfma_f32_16x16x32_bf16 v[72:75], v[176:179], v[200:203], v[72:75]
	v_mfma_f32_16x16x32_bf16 v[68:71], v[168:171], v[208:211], v[68:71]
	v_mfma_f32_16x16x32_bf16 v[64:67], v[176:179], v[208:211], v[64:67]
	v_mfma_f32_16x16x32_bf16 v[112:115], v[172:175], v[188:191], v[112:115]
	v_mfma_f32_16x16x32_bf16 v[104:107], v[180:183], v[188:191], v[104:107]
	v_mfma_f32_16x16x32_bf16 v[96:99], v[172:175], v[196:199], v[96:99]
	v_mfma_f32_16x16x32_bf16 v[88:91], v[180:183], v[196:199], v[88:91]
	v_mfma_f32_16x16x32_bf16 v[80:83], v[172:175], v[204:207], v[80:83]
	v_mfma_f32_16x16x32_bf16 v[72:75], v[180:183], v[204:207], v[72:75]
	v_mfma_f32_16x16x32_bf16 v[68:71], v[172:175], v[212:215], v[68:71]
	v_mfma_f32_16x16x32_bf16 v[64:67], v[180:183], v[212:215], v[64:67]
	s_barrier
	s_add_i32 s62, s50, s29
	s_mov_b32 m0, s62
	ds_read_b128 v[184:187], v151 offset:16384
	ds_read_b128 v[188:191], v151 offset:17408
	ds_read_b128 v[192:195], v151 offset:18432
	ds_read_b128 v[196:199], v151 offset:19456
	ds_read_b128 v[200:203], v151 offset:20480
	global_load_lds_dwordx4 v132, s[42:43]
	s_add_i32 m0, s62, 0x2000
	s_add_u32 s62, s42, 0x100000
	s_mov_b64 s[98:99], s[42:43]
	s_addc_u32 s63, s43, 0
	s_add_i32 s64, s51, s29
	global_load_lds_dwordx4 v128, s[98:99]
	s_mov_b32 m0, s64
	s_mov_b64 s[100:101], s[44:45]
	global_load_lds_dwordx4 v132, s[62:63]
	s_add_i32 m0, s64, 0x2000
	ds_read_b128 v[204:207], v151 offset:21504
	global_load_lds_dwordx4 v128, s[62:63]
	s_mov_b32 m0, s31
	ds_read_b128 v[208:211], v151 offset:22528
	global_load_lds_dwordx4 v134, s[100:101]
	s_mov_b32 m0, s33
	ds_read_b128 v[212:215], v151 offset:23552
	global_load_lds_dwordx4 v130, s[100:101]
	s_waitcnt vmcnt(8) lgkmcnt(0)
	s_barrier
	v_mfma_f32_16x16x32_bf16 v[60:63], v[152:155], v[184:187], v[60:63]
	v_mfma_f32_16x16x32_bf16 v[56:59], v[160:163], v[184:187], v[56:59]
	v_mfma_f32_16x16x32_bf16 v[52:55], v[152:155], v[192:195], v[52:55]
	v_mfma_f32_16x16x32_bf16 v[44:47], v[160:163], v[192:195], v[44:47]
	v_mfma_f32_16x16x32_bf16 v[36:39], v[152:155], v[200:203], v[36:39]
	v_mfma_f32_16x16x32_bf16 v[28:31], v[160:163], v[200:203], v[28:31]
	v_mfma_f32_16x16x32_bf16 v[20:23], v[152:155], v[208:211], v[20:23]
	v_mfma_f32_16x16x32_bf16 v[12:15], v[160:163], v[208:211], v[12:15]
	v_mfma_f32_16x16x32_bf16 v[60:63], v[156:159], v[188:191], v[60:63]
	v_mfma_f32_16x16x32_bf16 v[56:59], v[164:167], v[188:191], v[56:59]
	v_mfma_f32_16x16x32_bf16 v[52:55], v[156:159], v[196:199], v[52:55]
	v_mfma_f32_16x16x32_bf16 v[44:47], v[164:167], v[196:199], v[44:47]
	v_mfma_f32_16x16x32_bf16 v[36:39], v[156:159], v[204:207], v[36:39]
	v_mfma_f32_16x16x32_bf16 v[28:31], v[164:167], v[204:207], v[28:31]
	v_mfma_f32_16x16x32_bf16 v[20:23], v[156:159], v[212:215], v[20:23]
	v_mfma_f32_16x16x32_bf16 v[12:15], v[164:167], v[212:215], v[12:15]
	v_mfma_f32_16x16x32_bf16 v[48:51], v[168:171], v[184:187], v[48:51]
	v_mfma_f32_16x16x32_bf16 v[40:43], v[176:179], v[184:187], v[40:43]
	v_mfma_f32_16x16x32_bf16 v[32:35], v[168:171], v[192:195], v[32:35]
	v_mfma_f32_16x16x32_bf16 v[24:27], v[176:179], v[192:195], v[24:27]
	v_mfma_f32_16x16x32_bf16 v[16:19], v[168:171], v[200:203], v[16:19]
	v_mfma_f32_16x16x32_bf16 v[8:11], v[176:179], v[200:203], v[8:11]
	v_mfma_f32_16x16x32_bf16 v[4:7], v[168:171], v[208:211], v[4:7]
	v_mfma_f32_16x16x32_bf16 v[0:3], v[176:179], v[208:211], v[0:3]
	v_mfma_f32_16x16x32_bf16 v[48:51], v[172:175], v[188:191], v[48:51]
	v_mfma_f32_16x16x32_bf16 v[40:43], v[180:183], v[188:191], v[40:43]
	v_mfma_f32_16x16x32_bf16 v[32:35], v[172:175], v[196:199], v[32:35]
	v_mfma_f32_16x16x32_bf16 v[24:27], v[180:183], v[196:199], v[24:27]
	v_mfma_f32_16x16x32_bf16 v[16:19], v[172:175], v[204:207], v[16:19]
	v_mfma_f32_16x16x32_bf16 v[8:11], v[180:183], v[204:207], v[8:11]
	v_mfma_f32_16x16x32_bf16 v[4:7], v[172:175], v[212:215], v[4:7]
	v_mfma_f32_16x16x32_bf16 v[0:3], v[180:183], v[212:215], v[0:3]
	s_barrier
	s_add_i32 s62, 0, 0x18000
	s_add_i32 s63, 0, 0x1c000
	ds_read_b128 v[152:155], v149 offset:32768
	ds_read_b128 v[156:159], v149 offset:33792
	ds_read_b128 v[160:163], v149 offset:34816
	ds_read_b128 v[164:167], v149 offset:35840
	ds_read_b128 v[168:171], v150 offset:32768
	ds_read_b128 v[172:175], v150 offset:33792
	ds_read_b128 v[176:179], v150 offset:34816
	ds_read_b128 v[180:183], v150 offset:35840
	s_add_u32 s44, s44, 0x100000
	s_addc_u32 s45, s45, 0
	s_mov_b32 m0, s35
	ds_read_b128 v[184:187], v151 offset:32768
	ds_read_b128 v[188:191], v151 offset:33792
	ds_read_b128 v[192:195], v151 offset:34816
	ds_read_b128 v[196:199], v151 offset:35840
	ds_read_b128 v[200:203], v151 offset:36864
	ds_read_b128 v[204:207], v151 offset:37888
	ds_read_b128 v[208:211], v151 offset:38912
	global_load_lds_dwordx4 v134, s[44:45]
	s_mov_b32 m0, s39
	ds_read_b128 v[212:215], v151 offset:39936
	global_load_lds_dwordx4 v130, s[44:45]
	s_waitcnt vmcnt(8) lgkmcnt(0)
	s_barrier
	v_mfma_f32_16x16x32_bf16 v[124:127], v[152:155], v[184:187], v[124:127]
	v_mfma_f32_16x16x32_bf16 v[120:123], v[160:163], v[184:187], v[120:123]
	v_mfma_f32_16x16x32_bf16 v[116:119], v[152:155], v[192:195], v[116:119]
	v_mfma_f32_16x16x32_bf16 v[108:111], v[160:163], v[192:195], v[108:111]
	v_mfma_f32_16x16x32_bf16 v[100:103], v[152:155], v[200:203], v[100:103]
	v_mfma_f32_16x16x32_bf16 v[92:95], v[160:163], v[200:203], v[92:95]
	v_mfma_f32_16x16x32_bf16 v[84:87], v[152:155], v[208:211], v[84:87]
	v_mfma_f32_16x16x32_bf16 v[76:79], v[160:163], v[208:211], v[76:79]
	v_mfma_f32_16x16x32_bf16 v[124:127], v[156:159], v[188:191], v[124:127]
	v_mfma_f32_16x16x32_bf16 v[120:123], v[164:167], v[188:191], v[120:123]
	v_mfma_f32_16x16x32_bf16 v[116:119], v[156:159], v[196:199], v[116:119]
	v_mfma_f32_16x16x32_bf16 v[108:111], v[164:167], v[196:199], v[108:111]
	v_mfma_f32_16x16x32_bf16 v[100:103], v[156:159], v[204:207], v[100:103]
	v_mfma_f32_16x16x32_bf16 v[92:95], v[164:167], v[204:207], v[92:95]
	v_mfma_f32_16x16x32_bf16 v[84:87], v[156:159], v[212:215], v[84:87]
	v_mfma_f32_16x16x32_bf16 v[76:79], v[164:167], v[212:215], v[76:79]
	v_mfma_f32_16x16x32_bf16 v[112:115], v[168:171], v[184:187], v[112:115]
	v_mfma_f32_16x16x32_bf16 v[104:107], v[176:179], v[184:187], v[104:107]
	v_mfma_f32_16x16x32_bf16 v[96:99], v[168:171], v[192:195], v[96:99]
	v_mfma_f32_16x16x32_bf16 v[88:91], v[176:179], v[192:195], v[88:91]
	v_mfma_f32_16x16x32_bf16 v[80:83], v[168:171], v[200:203], v[80:83]
	v_mfma_f32_16x16x32_bf16 v[72:75], v[176:179], v[200:203], v[72:75]
	v_mfma_f32_16x16x32_bf16 v[68:71], v[168:171], v[208:211], v[68:71]
	v_mfma_f32_16x16x32_bf16 v[64:67], v[176:179], v[208:211], v[64:67]
	v_mfma_f32_16x16x32_bf16 v[112:115], v[172:175], v[188:191], v[112:115]
	v_mfma_f32_16x16x32_bf16 v[104:107], v[180:183], v[188:191], v[104:107]
	v_mfma_f32_16x16x32_bf16 v[96:99], v[172:175], v[196:199], v[96:99]
	v_mfma_f32_16x16x32_bf16 v[88:91], v[180:183], v[196:199], v[88:91]
	v_mfma_f32_16x16x32_bf16 v[80:83], v[172:175], v[204:207], v[80:83]
	v_mfma_f32_16x16x32_bf16 v[72:75], v[180:183], v[204:207], v[72:75]
	v_mfma_f32_16x16x32_bf16 v[68:71], v[172:175], v[212:215], v[68:71]
	v_mfma_f32_16x16x32_bf16 v[64:67], v[180:183], v[212:215], v[64:67]
	s_barrier
	s_add_i32 s44, s62, s29
	s_add_i32 m0, s44, -128
	ds_read_b128 v[184:187], v151 offset:49152
	ds_read_b128 v[188:191], v151 offset:50176
	ds_read_b128 v[192:195], v151 offset:51200
	ds_read_b128 v[196:199], v151 offset:52224
	global_load_lds_dwordx4 v132, s[42:43] offset:128
	s_add_i32 m0, s44, 8064
	s_add_u32 s42, s42, 0x100080
	s_addc_u32 s43, s43, 0
	s_add_i32 s44, s63, s29
	global_load_lds_dwordx4 v128, s[98:99] offset:128
	s_mov_b32 m0, s44
	ds_read_b128 v[200:203], v151 offset:53248
	global_load_lds_dwordx4 v132, s[42:43]
	s_add_i32 m0, s44, 0x2000
	ds_read_b128 v[204:207], v151 offset:54272
	global_load_lds_dwordx4 v128, s[42:43]
	s_add_i32 m0, s48, -128
	ds_read_b128 v[208:211], v151 offset:55296
	global_load_lds_dwordx4 v134, s[100:101] offset:128
	s_add_i32 m0, s49, -128
	ds_read_b128 v[212:215], v151 offset:56320
	global_load_lds_dwordx4 v130, s[100:101] offset:128
	s_waitcnt vmcnt(8) lgkmcnt(0)
	s_barrier
	v_mfma_f32_16x16x32_bf16 v[60:63], v[152:155], v[184:187], v[60:63]
	v_mfma_f32_16x16x32_bf16 v[56:59], v[160:163], v[184:187], v[56:59]
	v_mfma_f32_16x16x32_bf16 v[52:55], v[152:155], v[192:195], v[52:55]
	v_mfma_f32_16x16x32_bf16 v[44:47], v[160:163], v[192:195], v[44:47]
	v_mfma_f32_16x16x32_bf16 v[36:39], v[152:155], v[200:203], v[36:39]
	v_mfma_f32_16x16x32_bf16 v[28:31], v[160:163], v[200:203], v[28:31]
	v_mfma_f32_16x16x32_bf16 v[20:23], v[152:155], v[208:211], v[20:23]
	v_mfma_f32_16x16x32_bf16 v[12:15], v[160:163], v[208:211], v[12:15]
	v_mfma_f32_16x16x32_bf16 v[60:63], v[156:159], v[188:191], v[60:63]
	v_mfma_f32_16x16x32_bf16 v[56:59], v[164:167], v[188:191], v[56:59]
	v_mfma_f32_16x16x32_bf16 v[52:55], v[156:159], v[196:199], v[52:55]
	v_mfma_f32_16x16x32_bf16 v[44:47], v[164:167], v[196:199], v[44:47]
	v_mfma_f32_16x16x32_bf16 v[36:39], v[156:159], v[204:207], v[36:39]
	v_mfma_f32_16x16x32_bf16 v[28:31], v[164:167], v[204:207], v[28:31]
	v_mfma_f32_16x16x32_bf16 v[20:23], v[156:159], v[212:215], v[20:23]
	v_mfma_f32_16x16x32_bf16 v[12:15], v[164:167], v[212:215], v[12:15]
	v_mfma_f32_16x16x32_bf16 v[48:51], v[168:171], v[184:187], v[48:51]
	v_mfma_f32_16x16x32_bf16 v[40:43], v[176:179], v[184:187], v[40:43]
	v_mfma_f32_16x16x32_bf16 v[32:35], v[168:171], v[192:195], v[32:35]
	v_mfma_f32_16x16x32_bf16 v[24:27], v[176:179], v[192:195], v[24:27]
	v_mfma_f32_16x16x32_bf16 v[16:19], v[168:171], v[200:203], v[16:19]
	v_mfma_f32_16x16x32_bf16 v[8:11], v[176:179], v[200:203], v[8:11]
	v_mfma_f32_16x16x32_bf16 v[4:7], v[168:171], v[208:211], v[4:7]
	v_mfma_f32_16x16x32_bf16 v[0:3], v[176:179], v[208:211], v[0:3]
	v_mfma_f32_16x16x32_bf16 v[48:51], v[172:175], v[188:191], v[48:51]
	v_mfma_f32_16x16x32_bf16 v[40:43], v[180:183], v[188:191], v[40:43]
	v_mfma_f32_16x16x32_bf16 v[32:35], v[172:175], v[196:199], v[32:35]
	v_mfma_f32_16x16x32_bf16 v[24:27], v[180:183], v[196:199], v[24:27]
	v_mfma_f32_16x16x32_bf16 v[16:19], v[172:175], v[204:207], v[16:19]
	v_mfma_f32_16x16x32_bf16 v[8:11], v[180:183], v[204:207], v[8:11]
	v_mfma_f32_16x16x32_bf16 v[4:7], v[172:175], v[212:215], v[4:7]
	v_mfma_f32_16x16x32_bf16 v[0:3], v[180:183], v[212:215], v[0:3]
	s_barrier
	s_add_i32 s61, s61, 2
	s_add_u32 s40, s40, 0x100
	s_addc_u32 s41, s41, 0
	s_add_u32 s59, s59, 0x100
	s_addc_u32 s60, s60, 0
	s_cmp_gt_u32 s61, 61
	s_cbranch_scc0 .LBB0_622
	s_and_b64 vcc, exec, s[10:11]
	s_cbranch_vccz .LBB0_625
	s_barrier

.LBB0_773:
	ds_read_b128 v[144:147], v155
	ds_read_b128 v[148:151], v155 offset:1024
	ds_read_b128 v[158:161], v155 offset:2048
	ds_read_b128 v[162:165], v155 offset:3072
	ds_read_b128 v[166:169], v156
	ds_read_b128 v[170:173], v156 offset:1024
	ds_read_b128 v[174:177], v156 offset:2048
	ds_read_b128 v[178:181], v156 offset:3072
	s_add_u32 s36, s30, 0xfff80080
	s_addc_u32 s37, s31, -1
	s_cmp_eq_u32 s52, 28
	s_cselect_b32 s39, s23, s37
	s_cselect_b32 s38, s48, s36
	s_cselect_b32 s37, s21, s51
	s_cselect_b32 s36, s49, s50
	s_add_i32 m0, s17, 0xc000
	ds_read_b128 v[182:185], v157
	ds_read_b128 v[186:189], v157 offset:1024
	ds_read_b128 v[190:193], v157 offset:2048
	ds_read_b128 v[194:197], v157 offset:3072
	ds_read_b128 v[198:201], v157 offset:4096
	ds_read_b128 v[202:205], v157 offset:5120
	ds_read_b128 v[206:209], v157 offset:6144
	global_load_lds_dwordx4 v136, s[30:31]
	s_add_i32 m0, s17, 0xe000
	ds_read_b128 v[210:213], v157 offset:7168
	global_load_lds_dwordx4 v138, s[30:31]
	s_waitcnt vmcnt(8) lgkmcnt(0)
	s_barrier
	v_mfma_i32_16x16x64_i8 v[124:127], v[144:147], v[182:185], v[124:127]
	v_mfma_i32_16x16x64_i8 v[116:119], v[158:161], v[182:185], v[116:119]
	v_mfma_i32_16x16x64_i8 v[108:111], v[144:147], v[190:193], v[108:111]
	v_mfma_i32_16x16x64_i8 v[100:103], v[158:161], v[190:193], v[100:103]
	v_mfma_i32_16x16x64_i8 v[92:95], v[144:147], v[198:201], v[92:95]
	v_mfma_i32_16x16x64_i8 v[84:87], v[158:161], v[198:201], v[84:87]
	v_mfma_i32_16x16x64_i8 v[76:79], v[144:147], v[206:209], v[76:79]
	v_mfma_i32_16x16x64_i8 v[68:71], v[158:161], v[206:209], v[68:71]
	v_mfma_i32_16x16x64_i8 v[124:127], v[148:151], v[186:189], v[124:127]
	v_mfma_i32_16x16x64_i8 v[116:119], v[162:165], v[186:189], v[116:119]
	v_mfma_i32_16x16x64_i8 v[108:111], v[148:151], v[194:197], v[108:111]
	v_mfma_i32_16x16x64_i8 v[100:103], v[162:165], v[194:197], v[100:103]
	v_mfma_i32_16x16x64_i8 v[92:95], v[148:151], v[202:205], v[92:95]
	v_mfma_i32_16x16x64_i8 v[84:87], v[162:165], v[202:205], v[84:87]
	v_mfma_i32_16x16x64_i8 v[76:79], v[148:151], v[210:213], v[76:79]
	v_mfma_i32_16x16x64_i8 v[68:71], v[162:165], v[210:213], v[68:71]
	v_mfma_i32_16x16x64_i8 v[120:123], v[166:169], v[182:185], v[120:123]
	v_mfma_i32_16x16x64_i8 v[112:115], v[174:177], v[182:185], v[112:115]
	v_mfma_i32_16x16x64_i8 v[104:107], v[166:169], v[190:193], v[104:107]
	v_mfma_i32_16x16x64_i8 v[96:99], v[174:177], v[190:193], v[96:99]
	v_mfma_i32_16x16x64_i8 v[88:91], v[166:169], v[198:201], v[88:91]
	v_mfma_i32_16x16x64_i8 v[80:83], v[174:177], v[198:201], v[80:83]
	v_mfma_i32_16x16x64_i8 v[72:75], v[166:169], v[206:209], v[72:75]
	v_mfma_i32_16x16x64_i8 v[64:67], v[174:177], v[206:209], v[64:67]
	v_mfma_i32_16x16x64_i8 v[120:123], v[170:173], v[186:189], v[120:123]
	v_mfma_i32_16x16x64_i8 v[112:115], v[178:181], v[186:189], v[112:115]
	v_mfma_i32_16x16x64_i8 v[104:107], v[170:173], v[194:197], v[104:107]
	v_mfma_i32_16x16x64_i8 v[96:99], v[178:181], v[194:197], v[96:99]
	v_mfma_i32_16x16x64_i8 v[88:91], v[170:173], v[202:205], v[88:91]
	v_mfma_i32_16x16x64_i8 v[80:83], v[178:181], v[202:205], v[80:83]
	v_mfma_i32_16x16x64_i8 v[72:75], v[170:173], v[210:213], v[72:75]
	v_mfma_i32_16x16x64_i8 v[64:67], v[178:181], v[210:213], v[64:67]
	s_barrier
	s_add_i32 s53, s44, s2
	s_mov_b32 m0, s53
	ds_read_b128 v[182:185], v157 offset:16384
	ds_read_b128 v[186:189], v157 offset:17408
	ds_read_b128 v[190:193], v157 offset:18432
	ds_read_b128 v[194:197], v157 offset:19456
	ds_read_b128 v[198:201], v157 offset:20480
	global_load_lds_dwordx4 v132, s[36:37]
	s_add_i32 m0, s53, 0x2000
	s_add_u32 s54, s36, 0x80000
	s_mov_b64 s[98:99], s[36:37]
	s_addc_u32 s55, s37, 0
	s_add_i32 s53, s45, s2
	global_load_lds_dwordx4 v128, s[98:99]
	s_mov_b32 m0, s53
	s_mov_b64 s[100:101], s[38:39]
	global_load_lds_dwordx4 v132, s[54:55]
	s_add_i32 m0, s53, 0x2000
	ds_read_b128 v[202:205], v157 offset:21504
	global_load_lds_dwordx4 v128, s[54:55]
	s_mov_b32 m0, s17
	ds_read_b128 v[206:209], v157 offset:22528
	global_load_lds_dwordx4 v134, s[100:101]
	s_mov_b32 m0, s29
	ds_read_b128 v[210:213], v157 offset:23552
	global_load_lds_dwordx4 v130, s[100:101]
	s_waitcnt vmcnt(8) lgkmcnt(0)
	s_barrier
	v_mfma_i32_16x16x64_i8 v[60:63], v[144:147], v[182:185], v[60:63]
	v_mfma_i32_16x16x64_i8 v[52:55], v[158:161], v[182:185], v[52:55]
	v_mfma_i32_16x16x64_i8 v[44:47], v[144:147], v[190:193], v[44:47]
	v_mfma_i32_16x16x64_i8 v[36:39], v[158:161], v[190:193], v[36:39]
	v_mfma_i32_16x16x64_i8 v[28:31], v[144:147], v[198:201], v[28:31]
	v_mfma_i32_16x16x64_i8 v[20:23], v[158:161], v[198:201], v[20:23]
	v_mfma_i32_16x16x64_i8 v[12:15], v[144:147], v[206:209], v[12:15]
	v_mfma_i32_16x16x64_i8 v[4:7], v[158:161], v[206:209], v[4:7]
	v_mfma_i32_16x16x64_i8 v[60:63], v[148:151], v[186:189], v[60:63]
	v_mfma_i32_16x16x64_i8 v[52:55], v[162:165], v[186:189], v[52:55]
	v_mfma_i32_16x16x64_i8 v[44:47], v[148:151], v[194:197], v[44:47]
	v_mfma_i32_16x16x64_i8 v[36:39], v[162:165], v[194:197], v[36:39]
	v_mfma_i32_16x16x64_i8 v[28:31], v[148:151], v[202:205], v[28:31]
	v_mfma_i32_16x16x64_i8 v[20:23], v[162:165], v[202:205], v[20:23]
	v_mfma_i32_16x16x64_i8 v[12:15], v[148:151], v[210:213], v[12:15]
	v_mfma_i32_16x16x64_i8 v[4:7], v[162:165], v[210:213], v[4:7]
	v_mfma_i32_16x16x64_i8 v[56:59], v[166:169], v[182:185], v[56:59]
	v_mfma_i32_16x16x64_i8 v[48:51], v[174:177], v[182:185], v[48:51]
	v_mfma_i32_16x16x64_i8 v[40:43], v[166:169], v[190:193], v[40:43]
	v_mfma_i32_16x16x64_i8 v[32:35], v[174:177], v[190:193], v[32:35]
	v_mfma_i32_16x16x64_i8 v[24:27], v[166:169], v[198:201], v[24:27]
	v_mfma_i32_16x16x64_i8 v[16:19], v[174:177], v[198:201], v[16:19]
	v_mfma_i32_16x16x64_i8 v[8:11], v[166:169], v[206:209], v[8:11]
	v_mfma_i32_16x16x64_i8 v[0:3], v[174:177], v[206:209], v[0:3]
	v_mfma_i32_16x16x64_i8 v[56:59], v[170:173], v[186:189], v[56:59]
	v_mfma_i32_16x16x64_i8 v[48:51], v[178:181], v[186:189], v[48:51]
	v_mfma_i32_16x16x64_i8 v[40:43], v[170:173], v[194:197], v[40:43]
	v_mfma_i32_16x16x64_i8 v[32:35], v[178:181], v[194:197], v[32:35]
	v_mfma_i32_16x16x64_i8 v[24:27], v[170:173], v[202:205], v[24:27]
	v_mfma_i32_16x16x64_i8 v[16:19], v[178:181], v[202:205], v[16:19]
	v_mfma_i32_16x16x64_i8 v[8:11], v[170:173], v[210:213], v[8:11]
	v_mfma_i32_16x16x64_i8 v[0:3], v[178:181], v[210:213], v[0:3]
	s_barrier
	s_add_i32 s53, 0, 0x18000
	s_add_i32 s54, 0, 0x1c000
	ds_read_b128 v[144:147], v155 offset:32768
	ds_read_b128 v[148:151], v155 offset:33792
	ds_read_b128 v[158:161], v155 offset:34816
	ds_read_b128 v[162:165], v155 offset:35840
	ds_read_b128 v[166:169], v156 offset:32768
	ds_read_b128 v[170:173], v156 offset:33792
	ds_read_b128 v[174:177], v156 offset:34816
	ds_read_b128 v[178:181], v156 offset:35840
	s_add_u32 s38, s38, 0x80000
	s_addc_u32 s39, s39, 0
	s_mov_b32 m0, s33
	ds_read_b128 v[182:185], v157 offset:32768
	ds_read_b128 v[186:189], v157 offset:33792
	ds_read_b128 v[190:193], v157 offset:34816
	ds_read_b128 v[194:197], v157 offset:35840
	ds_read_b128 v[198:201], v157 offset:36864
	ds_read_b128 v[202:205], v157 offset:37888
	ds_read_b128 v[206:209], v157 offset:38912
	global_load_lds_dwordx4 v134, s[38:39]
	s_mov_b32 m0, s35
	ds_read_b128 v[210:213], v157 offset:39936
	global_load_lds_dwordx4 v130, s[38:39]
	s_waitcnt vmcnt(8) lgkmcnt(0)
	s_barrier
	v_mfma_i32_16x16x64_i8 v[124:127], v[144:147], v[182:185], v[124:127]
	v_mfma_i32_16x16x64_i8 v[116:119], v[158:161], v[182:185], v[116:119]
	v_mfma_i32_16x16x64_i8 v[108:111], v[144:147], v[190:193], v[108:111]
	v_mfma_i32_16x16x64_i8 v[100:103], v[158:161], v[190:193], v[100:103]
	v_mfma_i32_16x16x64_i8 v[92:95], v[144:147], v[198:201], v[92:95]
	v_mfma_i32_16x16x64_i8 v[84:87], v[158:161], v[198:201], v[84:87]
	v_mfma_i32_16x16x64_i8 v[76:79], v[144:147], v[206:209], v[76:79]
	v_mfma_i32_16x16x64_i8 v[68:71], v[158:161], v[206:209], v[68:71]
	v_mfma_i32_16x16x64_i8 v[124:127], v[148:151], v[186:189], v[124:127]
	v_mfma_i32_16x16x64_i8 v[116:119], v[162:165], v[186:189], v[116:119]
	v_mfma_i32_16x16x64_i8 v[108:111], v[148:151], v[194:197], v[108:111]
	v_mfma_i32_16x16x64_i8 v[100:103], v[162:165], v[194:197], v[100:103]
	v_mfma_i32_16x16x64_i8 v[92:95], v[148:151], v[202:205], v[92:95]
	v_mfma_i32_16x16x64_i8 v[84:87], v[162:165], v[202:205], v[84:87]
	v_mfma_i32_16x16x64_i8 v[76:79], v[148:151], v[210:213], v[76:79]
	v_mfma_i32_16x16x64_i8 v[68:71], v[162:165], v[210:213], v[68:71]
	v_mfma_i32_16x16x64_i8 v[120:123], v[166:169], v[182:185], v[120:123]
	v_mfma_i32_16x16x64_i8 v[112:115], v[174:177], v[182:185], v[112:115]
	v_mfma_i32_16x16x64_i8 v[104:107], v[166:169], v[190:193], v[104:107]
	v_mfma_i32_16x16x64_i8 v[96:99], v[174:177], v[190:193], v[96:99]
	v_mfma_i32_16x16x64_i8 v[88:91], v[166:169], v[198:201], v[88:91]
	v_mfma_i32_16x16x64_i8 v[80:83], v[174:177], v[198:201], v[80:83]
	v_mfma_i32_16x16x64_i8 v[72:75], v[166:169], v[206:209], v[72:75]
	v_mfma_i32_16x16x64_i8 v[64:67], v[174:177], v[206:209], v[64:67]
	v_mfma_i32_16x16x64_i8 v[120:123], v[170:173], v[186:189], v[120:123]
	v_mfma_i32_16x16x64_i8 v[112:115], v[178:181], v[186:189], v[112:115]
	v_mfma_i32_16x16x64_i8 v[104:107], v[170:173], v[194:197], v[104:107]
	v_mfma_i32_16x16x64_i8 v[96:99], v[178:181], v[194:197], v[96:99]
	v_mfma_i32_16x16x64_i8 v[88:91], v[170:173], v[202:205], v[88:91]
	v_mfma_i32_16x16x64_i8 v[80:83], v[178:181], v[202:205], v[80:83]
	v_mfma_i32_16x16x64_i8 v[72:75], v[170:173], v[210:213], v[72:75]
	v_mfma_i32_16x16x64_i8 v[64:67], v[178:181], v[210:213], v[64:67]
	s_barrier
	s_add_i32 s38, s53, s2
	s_add_i32 m0, s38, -128
	ds_read_b128 v[182:185], v157 offset:49152
	ds_read_b128 v[186:189], v157 offset:50176
	ds_read_b128 v[190:193], v157 offset:51200
	ds_read_b128 v[194:197], v157 offset:52224
	global_load_lds_dwordx4 v132, s[36:37] offset:128
	s_add_i32 m0, s38, 8064
	s_add_u32 s36, s36, 0x80080
	s_addc_u32 s37, s37, 0
	s_add_i32 s38, s54, s2
	global_load_lds_dwordx4 v128, s[98:99] offset:128
	s_mov_b32 m0, s38
	ds_read_b128 v[198:201], v157 offset:53248
	global_load_lds_dwordx4 v132, s[36:37]
	s_add_i32 m0, s38, 0x2000
	ds_read_b128 v[202:205], v157 offset:54272
	global_load_lds_dwordx4 v128, s[36:37]
	s_add_i32 m0, s42, -128
	ds_read_b128 v[206:209], v157 offset:55296
	global_load_lds_dwordx4 v134, s[100:101] offset:128
	s_add_i32 m0, s43, -128
	ds_read_b128 v[210:213], v157 offset:56320
	global_load_lds_dwordx4 v130, s[100:101] offset:128
	s_waitcnt vmcnt(8) lgkmcnt(0)
	s_barrier
	v_mfma_i32_16x16x64_i8 v[60:63], v[144:147], v[182:185], v[60:63]
	v_mfma_i32_16x16x64_i8 v[52:55], v[158:161], v[182:185], v[52:55]
	v_mfma_i32_16x16x64_i8 v[44:47], v[144:147], v[190:193], v[44:47]
	v_mfma_i32_16x16x64_i8 v[36:39], v[158:161], v[190:193], v[36:39]
	v_mfma_i32_16x16x64_i8 v[28:31], v[144:147], v[198:201], v[28:31]
	v_mfma_i32_16x16x64_i8 v[20:23], v[158:161], v[198:201], v[20:23]
	v_mfma_i32_16x16x64_i8 v[12:15], v[144:147], v[206:209], v[12:15]
	v_mfma_i32_16x16x64_i8 v[4:7], v[158:161], v[206:209], v[4:7]
	v_mfma_i32_16x16x64_i8 v[60:63], v[148:151], v[186:189], v[60:63]
	v_mfma_i32_16x16x64_i8 v[52:55], v[162:165], v[186:189], v[52:55]
	v_mfma_i32_16x16x64_i8 v[44:47], v[148:151], v[194:197], v[44:47]
	v_mfma_i32_16x16x64_i8 v[36:39], v[162:165], v[194:197], v[36:39]
	v_mfma_i32_16x16x64_i8 v[28:31], v[148:151], v[202:205], v[28:31]
	v_mfma_i32_16x16x64_i8 v[20:23], v[162:165], v[202:205], v[20:23]
	v_mfma_i32_16x16x64_i8 v[12:15], v[148:151], v[210:213], v[12:15]
	v_mfma_i32_16x16x64_i8 v[4:7], v[162:165], v[210:213], v[4:7]
	v_mfma_i32_16x16x64_i8 v[56:59], v[166:169], v[182:185], v[56:59]
	v_mfma_i32_16x16x64_i8 v[48:51], v[174:177], v[182:185], v[48:51]
	v_mfma_i32_16x16x64_i8 v[40:43], v[166:169], v[190:193], v[40:43]
	v_mfma_i32_16x16x64_i8 v[32:35], v[174:177], v[190:193], v[32:35]
	v_mfma_i32_16x16x64_i8 v[24:27], v[166:169], v[198:201], v[24:27]
	v_mfma_i32_16x16x64_i8 v[16:19], v[174:177], v[198:201], v[16:19]
	v_mfma_i32_16x16x64_i8 v[8:11], v[166:169], v[206:209], v[8:11]
	v_mfma_i32_16x16x64_i8 v[0:3], v[174:177], v[206:209], v[0:3]
	v_mfma_i32_16x16x64_i8 v[56:59], v[170:173], v[186:189], v[56:59]
	v_mfma_i32_16x16x64_i8 v[48:51], v[178:181], v[186:189], v[48:51]
	v_mfma_i32_16x16x64_i8 v[40:43], v[170:173], v[194:197], v[40:43]
	v_mfma_i32_16x16x64_i8 v[32:35], v[178:181], v[194:197], v[32:35]
	v_mfma_i32_16x16x64_i8 v[24:27], v[170:173], v[202:205], v[24:27]
	v_mfma_i32_16x16x64_i8 v[16:19], v[178:181], v[202:205], v[16:19]
	v_mfma_i32_16x16x64_i8 v[8:11], v[170:173], v[210:213], v[8:11]
	v_mfma_i32_16x16x64_i8 v[0:3], v[178:181], v[210:213], v[0:3]
	s_barrier
	s_add_i32 s52, s52, 2
	s_add_u32 s30, s30, 0x100
	s_addc_u32 s31, s31, 0
	s_add_u32 s50, s50, 0x100
	s_addc_u32 s51, s51, 0
	s_cmp_gt_u32 s52, 29
	s_cbranch_scc0 .LBB0_773
	s_and_b64 vcc, exec, s[14:15]
	s_cbranch_vccz .LBB0_776
	s_barrier

.LBB0_858:
	ds_read_b128 v[152:155], v149
	ds_read_b128 v[156:159], v149 offset:1024
	ds_read_b128 v[160:163], v149 offset:2048
	ds_read_b128 v[164:167], v149 offset:3072
	ds_read_b128 v[168:171], v150
	ds_read_b128 v[172:175], v150 offset:1024
	ds_read_b128 v[176:179], v150 offset:2048
	ds_read_b128 v[180:183], v150 offset:3072
	s_add_u32 s26, s24, 0x100
	s_addc_u32 s27, s25, 0
	s_cmpk_eq_i32 s54, 0xa8
	s_cselect_b32 s31, s5, s27
	s_cselect_b32 s30, s4, s26
	s_cselect_b32 s29, s23, s53
	s_cselect_b32 s28, s22, s52
	s_add_i32 m0, s33, 0xc000
	ds_read_b128 v[184:187], v151
	ds_read_b128 v[188:191], v151 offset:1024
	ds_read_b128 v[192:195], v151 offset:2048
	ds_read_b128 v[196:199], v151 offset:3072
	ds_read_b128 v[200:203], v151 offset:4096
	ds_read_b128 v[204:207], v151 offset:5120
	ds_read_b128 v[208:211], v151 offset:6144
	global_load_lds_dwordx4 v136, s[24:25]
	s_add_i32 m0, s33, 0xe000
	ds_read_b128 v[212:215], v151 offset:7168
	global_load_lds_dwordx4 v138, s[24:25]
	s_waitcnt vmcnt(8) lgkmcnt(0)
	s_barrier
	v_mfma_f32_16x16x32_bf16 v[124:127], v[152:155], v[184:187], v[124:127]
	v_mfma_f32_16x16x32_bf16 v[120:123], v[160:163], v[184:187], v[120:123]
	v_mfma_f32_16x16x32_bf16 v[116:119], v[152:155], v[192:195], v[116:119]
	v_mfma_f32_16x16x32_bf16 v[108:111], v[160:163], v[192:195], v[108:111]
	v_mfma_f32_16x16x32_bf16 v[100:103], v[152:155], v[200:203], v[100:103]
	v_mfma_f32_16x16x32_bf16 v[92:95], v[160:163], v[200:203], v[92:95]
	v_mfma_f32_16x16x32_bf16 v[84:87], v[152:155], v[208:211], v[84:87]
	v_mfma_f32_16x16x32_bf16 v[76:79], v[160:163], v[208:211], v[76:79]
	v_mfma_f32_16x16x32_bf16 v[124:127], v[156:159], v[188:191], v[124:127]
	v_mfma_f32_16x16x32_bf16 v[120:123], v[164:167], v[188:191], v[120:123]
	v_mfma_f32_16x16x32_bf16 v[116:119], v[156:159], v[196:199], v[116:119]
	v_mfma_f32_16x16x32_bf16 v[108:111], v[164:167], v[196:199], v[108:111]
	v_mfma_f32_16x16x32_bf16 v[100:103], v[156:159], v[204:207], v[100:103]
	v_mfma_f32_16x16x32_bf16 v[92:95], v[164:167], v[204:207], v[92:95]
	v_mfma_f32_16x16x32_bf16 v[84:87], v[156:159], v[212:215], v[84:87]
	v_mfma_f32_16x16x32_bf16 v[76:79], v[164:167], v[212:215], v[76:79]
	v_mfma_f32_16x16x32_bf16 v[112:115], v[168:171], v[184:187], v[112:115]
	v_mfma_f32_16x16x32_bf16 v[104:107], v[176:179], v[184:187], v[104:107]
	v_mfma_f32_16x16x32_bf16 v[96:99], v[168:171], v[192:195], v[96:99]
	v_mfma_f32_16x16x32_bf16 v[88:91], v[176:179], v[192:195], v[88:91]
	v_mfma_f32_16x16x32_bf16 v[80:83], v[168:171], v[200:203], v[80:83]
	v_mfma_f32_16x16x32_bf16 v[72:75], v[176:179], v[200:203], v[72:75]
	v_mfma_f32_16x16x32_bf16 v[68:71], v[168:171], v[208:211], v[68:71]
	v_mfma_f32_16x16x32_bf16 v[64:67], v[176:179], v[208:211], v[64:67]
	v_mfma_f32_16x16x32_bf16 v[112:115], v[172:175], v[188:191], v[112:115]
	v_mfma_f32_16x16x32_bf16 v[104:107], v[180:183], v[188:191], v[104:107]
	v_mfma_f32_16x16x32_bf16 v[96:99], v[172:175], v[196:199], v[96:99]
	v_mfma_f32_16x16x32_bf16 v[88:91], v[180:183], v[196:199], v[88:91]
	v_mfma_f32_16x16x32_bf16 v[80:83], v[172:175], v[204:207], v[80:83]
	v_mfma_f32_16x16x32_bf16 v[72:75], v[180:183], v[204:207], v[72:75]
	v_mfma_f32_16x16x32_bf16 v[68:71], v[172:175], v[212:215], v[68:71]
	v_mfma_f32_16x16x32_bf16 v[64:67], v[180:183], v[212:215], v[64:67]
	s_barrier
	s_add_i32 s24, s42, s2
	s_mov_b32 m0, s24
	ds_read_b128 v[184:187], v151 offset:16384
	ds_read_b128 v[188:191], v151 offset:17408
	ds_read_b128 v[192:195], v151 offset:18432
	ds_read_b128 v[196:199], v151 offset:19456
	global_load_lds_dwordx4 v132, s[28:29]
	s_add_i32 m0, s24, 0x2000
	s_add_u32 s24, s28, 0x2b0000
	s_mov_b64 s[98:99], s[28:29]
	s_addc_u32 s25, s29, 0
	s_add_i32 s55, s43, s2
	global_load_lds_dwordx4 v128, s[98:99]
	s_mov_b32 m0, s55
	ds_read_b128 v[200:203], v151 offset:20480
	global_load_lds_dwordx4 v132, s[24:25]
	s_add_i32 m0, s55, 0x2000
	ds_read_b128 v[204:207], v151 offset:21504
	global_load_lds_dwordx4 v128, s[24:25]
	s_mov_b32 m0, s33
	ds_read_b128 v[208:211], v151 offset:22528
	global_load_lds_dwordx4 v134, s[30:31]
	s_mov_b32 m0, s35
	ds_read_b128 v[212:215], v151 offset:23552
	global_load_lds_dwordx4 v130, s[30:31]
	s_waitcnt vmcnt(8) lgkmcnt(0)
	s_barrier
	v_mfma_f32_16x16x32_bf16 v[60:63], v[152:155], v[184:187], v[60:63]
	v_mfma_f32_16x16x32_bf16 v[56:59], v[160:163], v[184:187], v[56:59]
	v_mfma_f32_16x16x32_bf16 v[52:55], v[152:155], v[192:195], v[52:55]
	v_mfma_f32_16x16x32_bf16 v[44:47], v[160:163], v[192:195], v[44:47]
	v_mfma_f32_16x16x32_bf16 v[36:39], v[152:155], v[200:203], v[36:39]
	v_mfma_f32_16x16x32_bf16 v[28:31], v[160:163], v[200:203], v[28:31]
	v_mfma_f32_16x16x32_bf16 v[20:23], v[152:155], v[208:211], v[20:23]
	v_mfma_f32_16x16x32_bf16 v[12:15], v[160:163], v[208:211], v[12:15]
	v_mfma_f32_16x16x32_bf16 v[60:63], v[156:159], v[188:191], v[60:63]
	v_mfma_f32_16x16x32_bf16 v[56:59], v[164:167], v[188:191], v[56:59]
	v_mfma_f32_16x16x32_bf16 v[52:55], v[156:159], v[196:199], v[52:55]
	v_mfma_f32_16x16x32_bf16 v[44:47], v[164:167], v[196:199], v[44:47]
	v_mfma_f32_16x16x32_bf16 v[36:39], v[156:159], v[204:207], v[36:39]
	v_mfma_f32_16x16x32_bf16 v[28:31], v[164:167], v[204:207], v[28:31]
	v_mfma_f32_16x16x32_bf16 v[20:23], v[156:159], v[212:215], v[20:23]
	v_mfma_f32_16x16x32_bf16 v[12:15], v[164:167], v[212:215], v[12:15]
	v_mfma_f32_16x16x32_bf16 v[48:51], v[168:171], v[184:187], v[48:51]
	v_mfma_f32_16x16x32_bf16 v[40:43], v[176:179], v[184:187], v[40:43]
	v_mfma_f32_16x16x32_bf16 v[32:35], v[168:171], v[192:195], v[32:35]
	v_mfma_f32_16x16x32_bf16 v[24:27], v[176:179], v[192:195], v[24:27]
	v_mfma_f32_16x16x32_bf16 v[16:19], v[168:171], v[200:203], v[16:19]
	v_mfma_f32_16x16x32_bf16 v[8:11], v[176:179], v[200:203], v[8:11]
	v_mfma_f32_16x16x32_bf16 v[4:7], v[168:171], v[208:211], v[4:7]
	v_mfma_f32_16x16x32_bf16 v[0:3], v[176:179], v[208:211], v[0:3]
	v_mfma_f32_16x16x32_bf16 v[48:51], v[172:175], v[188:191], v[48:51]
	v_mfma_f32_16x16x32_bf16 v[40:43], v[180:183], v[188:191], v[40:43]
	v_mfma_f32_16x16x32_bf16 v[32:35], v[172:175], v[196:199], v[32:35]
	v_mfma_f32_16x16x32_bf16 v[24:27], v[180:183], v[196:199], v[24:27]
	v_mfma_f32_16x16x32_bf16 v[16:19], v[172:175], v[204:207], v[16:19]
	v_mfma_f32_16x16x32_bf16 v[8:11], v[180:183], v[204:207], v[8:11]
	v_mfma_f32_16x16x32_bf16 v[4:7], v[172:175], v[212:215], v[4:7]
	v_mfma_f32_16x16x32_bf16 v[0:3], v[180:183], v[212:215], v[0:3]
	s_barrier
	s_add_i32 s55, 0, 0x18000
	s_add_i32 s58, 0, 0x1c000
	ds_read_b128 v[152:155], v149 offset:32768
	ds_read_b128 v[156:159], v149 offset:33792
	ds_read_b128 v[160:163], v149 offset:34816
	ds_read_b128 v[164:167], v149 offset:35840
	ds_read_b128 v[168:171], v150 offset:32768
	ds_read_b128 v[172:175], v150 offset:33792
	ds_read_b128 v[176:179], v150 offset:34816
	ds_read_b128 v[180:183], v150 offset:35840
	s_add_u32 s24, s30, 0x2b0000
	s_addc_u32 s25, s31, 0
	s_mov_b32 m0, s36
	ds_read_b128 v[184:187], v151 offset:32768
	ds_read_b128 v[188:191], v151 offset:33792
	ds_read_b128 v[192:195], v151 offset:34816
	ds_read_b128 v[196:199], v151 offset:35840
	ds_read_b128 v[200:203], v151 offset:36864
	ds_read_b128 v[204:207], v151 offset:37888
	ds_read_b128 v[208:211], v151 offset:38912
	global_load_lds_dwordx4 v134, s[24:25]
	s_mov_b32 m0, s37
	ds_read_b128 v[212:215], v151 offset:39936
	global_load_lds_dwordx4 v130, s[24:25]
	s_waitcnt vmcnt(8) lgkmcnt(0)
	s_barrier
	v_mfma_f32_16x16x32_bf16 v[124:127], v[152:155], v[184:187], v[124:127]
	v_mfma_f32_16x16x32_bf16 v[120:123], v[160:163], v[184:187], v[120:123]
	v_mfma_f32_16x16x32_bf16 v[116:119], v[152:155], v[192:195], v[116:119]
	v_mfma_f32_16x16x32_bf16 v[108:111], v[160:163], v[192:195], v[108:111]
	v_mfma_f32_16x16x32_bf16 v[100:103], v[152:155], v[200:203], v[100:103]
	v_mfma_f32_16x16x32_bf16 v[92:95], v[160:163], v[200:203], v[92:95]
	v_mfma_f32_16x16x32_bf16 v[84:87], v[152:155], v[208:211], v[84:87]
	v_mfma_f32_16x16x32_bf16 v[76:79], v[160:163], v[208:211], v[76:79]
	v_mfma_f32_16x16x32_bf16 v[124:127], v[156:159], v[188:191], v[124:127]
	v_mfma_f32_16x16x32_bf16 v[120:123], v[164:167], v[188:191], v[120:123]
	v_mfma_f32_16x16x32_bf16 v[116:119], v[156:159], v[196:199], v[116:119]
	v_mfma_f32_16x16x32_bf16 v[108:111], v[164:167], v[196:199], v[108:111]
	v_mfma_f32_16x16x32_bf16 v[100:103], v[156:159], v[204:207], v[100:103]
	v_mfma_f32_16x16x32_bf16 v[92:95], v[164:167], v[204:207], v[92:95]
	v_mfma_f32_16x16x32_bf16 v[84:87], v[156:159], v[212:215], v[84:87]
	v_mfma_f32_16x16x32_bf16 v[76:79], v[164:167], v[212:215], v[76:79]
	v_mfma_f32_16x16x32_bf16 v[112:115], v[168:171], v[184:187], v[112:115]
	v_mfma_f32_16x16x32_bf16 v[104:107], v[176:179], v[184:187], v[104:107]
	v_mfma_f32_16x16x32_bf16 v[96:99], v[168:171], v[192:195], v[96:99]
	v_mfma_f32_16x16x32_bf16 v[88:91], v[176:179], v[192:195], v[88:91]
	v_mfma_f32_16x16x32_bf16 v[80:83], v[168:171], v[200:203], v[80:83]
	v_mfma_f32_16x16x32_bf16 v[72:75], v[176:179], v[200:203], v[72:75]
	v_mfma_f32_16x16x32_bf16 v[68:71], v[168:171], v[208:211], v[68:71]
	v_mfma_f32_16x16x32_bf16 v[64:67], v[176:179], v[208:211], v[64:67]
	v_mfma_f32_16x16x32_bf16 v[112:115], v[172:175], v[188:191], v[112:115]
	v_mfma_f32_16x16x32_bf16 v[104:107], v[180:183], v[188:191], v[104:107]
	v_mfma_f32_16x16x32_bf16 v[96:99], v[172:175], v[196:199], v[96:99]
	v_mfma_f32_16x16x32_bf16 v[88:91], v[180:183], v[196:199], v[88:91]
	v_mfma_f32_16x16x32_bf16 v[80:83], v[172:175], v[204:207], v[80:83]
	v_mfma_f32_16x16x32_bf16 v[72:75], v[180:183], v[204:207], v[72:75]
	v_mfma_f32_16x16x32_bf16 v[68:71], v[172:175], v[212:215], v[68:71]
	v_mfma_f32_16x16x32_bf16 v[64:67], v[180:183], v[212:215], v[64:67]
	s_barrier
	s_add_i32 s24, s55, s2
	s_add_i32 m0, s24, -128
	ds_read_b128 v[184:187], v151 offset:49152
	ds_read_b128 v[188:191], v151 offset:50176
	ds_read_b128 v[192:195], v151 offset:51200
	ds_read_b128 v[196:199], v151 offset:52224
	global_load_lds_dwordx4 v132, s[28:29] offset:128
	s_add_i32 m0, s24, 8064
	s_add_u32 s24, s28, 0x2b0080
	s_addc_u32 s25, s29, 0
	s_add_i32 s28, s58, s2
	global_load_lds_dwordx4 v128, s[98:99] offset:128
	s_mov_b32 m0, s28
	ds_read_b128 v[200:203], v151 offset:53248
	global_load_lds_dwordx4 v132, s[24:25]
	s_add_i32 m0, s28, 0x2000
	ds_read_b128 v[204:207], v151 offset:54272
	global_load_lds_dwordx4 v128, s[24:25]
	s_add_i32 m0, s40, -128
	ds_read_b128 v[208:211], v151 offset:55296
	global_load_lds_dwordx4 v134, s[30:31] offset:128
	s_add_i32 m0, s41, -128
	ds_read_b128 v[212:215], v151 offset:56320
	global_load_lds_dwordx4 v130, s[30:31] offset:128
	s_waitcnt vmcnt(8) lgkmcnt(0)
	s_barrier
	v_mfma_f32_16x16x32_bf16 v[60:63], v[152:155], v[184:187], v[60:63]
	v_mfma_f32_16x16x32_bf16 v[56:59], v[160:163], v[184:187], v[56:59]
	v_mfma_f32_16x16x32_bf16 v[52:55], v[152:155], v[192:195], v[52:55]
	v_mfma_f32_16x16x32_bf16 v[44:47], v[160:163], v[192:195], v[44:47]
	v_mfma_f32_16x16x32_bf16 v[36:39], v[152:155], v[200:203], v[36:39]
	v_mfma_f32_16x16x32_bf16 v[28:31], v[160:163], v[200:203], v[28:31]
	v_mfma_f32_16x16x32_bf16 v[20:23], v[152:155], v[208:211], v[20:23]
	v_mfma_f32_16x16x32_bf16 v[12:15], v[160:163], v[208:211], v[12:15]
	v_mfma_f32_16x16x32_bf16 v[60:63], v[156:159], v[188:191], v[60:63]
	v_mfma_f32_16x16x32_bf16 v[56:59], v[164:167], v[188:191], v[56:59]
	v_mfma_f32_16x16x32_bf16 v[52:55], v[156:159], v[196:199], v[52:55]
	v_mfma_f32_16x16x32_bf16 v[44:47], v[164:167], v[196:199], v[44:47]
	v_mfma_f32_16x16x32_bf16 v[36:39], v[156:159], v[204:207], v[36:39]
	v_mfma_f32_16x16x32_bf16 v[28:31], v[164:167], v[204:207], v[28:31]
	v_mfma_f32_16x16x32_bf16 v[20:23], v[156:159], v[212:215], v[20:23]
	v_mfma_f32_16x16x32_bf16 v[12:15], v[164:167], v[212:215], v[12:15]
	v_mfma_f32_16x16x32_bf16 v[48:51], v[168:171], v[184:187], v[48:51]
	v_mfma_f32_16x16x32_bf16 v[40:43], v[176:179], v[184:187], v[40:43]
	v_mfma_f32_16x16x32_bf16 v[32:35], v[168:171], v[192:195], v[32:35]
	v_mfma_f32_16x16x32_bf16 v[24:27], v[176:179], v[192:195], v[24:27]
	v_mfma_f32_16x16x32_bf16 v[16:19], v[168:171], v[200:203], v[16:19]
	v_mfma_f32_16x16x32_bf16 v[8:11], v[176:179], v[200:203], v[8:11]
	v_mfma_f32_16x16x32_bf16 v[4:7], v[168:171], v[208:211], v[4:7]
	v_mfma_f32_16x16x32_bf16 v[0:3], v[176:179], v[208:211], v[0:3]
	v_mfma_f32_16x16x32_bf16 v[48:51], v[172:175], v[188:191], v[48:51]
	v_mfma_f32_16x16x32_bf16 v[40:43], v[180:183], v[188:191], v[40:43]
	v_mfma_f32_16x16x32_bf16 v[32:35], v[172:175], v[196:199], v[32:35]
	v_mfma_f32_16x16x32_bf16 v[24:27], v[180:183], v[196:199], v[24:27]
	v_mfma_f32_16x16x32_bf16 v[16:19], v[172:175], v[204:207], v[16:19]
	v_mfma_f32_16x16x32_bf16 v[8:11], v[180:183], v[204:207], v[8:11]
	v_mfma_f32_16x16x32_bf16 v[4:7], v[172:175], v[212:215], v[4:7]
	v_mfma_f32_16x16x32_bf16 v[0:3], v[180:183], v[212:215], v[0:3]
	s_barrier
	s_add_i32 s54, s54, 2
	s_add_u32 s52, s52, 0x100
	s_addc_u32 s53, s53, 0
	s_cmpk_gt_u32 s54, 0xa9
	s_mov_b64 s[24:25], s[26:27]
	s_cbranch_scc0 .LBB0_858
	s_and_b64 vcc, exec, s[10:11]
	s_cbranch_vccz .LBB0_861
	s_barrier
